# k7 plus K-loop MFMAs reordered so each accumulator's two K-halves issue back to back (SrcC forwarding)
# speedup vs baseline: 1.0130x; 1.0130x over previous
; #define PG8_STAGE(bufoff, gbase, voff) do { _Pragma("unroll") for (int _i = 0; _i < 2; ++_i) \
;         __builtin_amdgcn_global_load_lds((const unsigned*)((const char*)(gbase) + (voff)[_i]), (LAS unsigned*)(lds + (bufoff) + ldsw + _i * 8192), 16, 0, 0); } while (0)
; #define PG8_LDA(dst, b, h) do { _Pragma("unroll") for (int m = 0; m < 4; ++m) _Pragma("unroll") for (int k = 0; k < 2; ++k) dst[m][k] = *(const LAS bf16x8*)(lds + PG8_SA(b, h) + aoff + m * 2048 + k * 1024); } while (0)
; #define PG8_LDB(dst, b, h) do { _Pragma("unroll") for (int n = 0; n < 2; ++n) _Pragma("unroll") for (int k = 0; k < 2; ++k) dst[n][k] = *(const LAS bf16x8*)(lds + PG8_SB(b, h) + boff + n * 2048 + k * 1024); } while (0)
; #define PG8_MMA(ai, bj, At, Bt) do { __builtin_amdgcn_s_setprio(1); _Pragma("unroll") for (int m = 0; m < 4; ++m) _Pragma("unroll") for (int n = 0; n < 2; ++n) _Pragma("unroll") for (int k = 0; k < 2; ++k) \
;         acc[ai][bj][m][n] = __builtin_amdgcn_mfma_f32_16x16x32_bf16(Bt[n][k], At[m][k], acc[ai][bj][m][n], 0, 0, 0); __builtin_amdgcn_s_setprio(0); } while (0)
; #define PG8_WAIT_V(n) asm volatile("s_waitcnt vmcnt(" #n ")" ::: "memory")
; #define PG8_WAIT_L(n) asm volatile("s_waitcnt lgkmcnt(" #n ")" ::: "memory")
; #define PG8_BAR __builtin_amdgcn_s_barrier()
; #define PG8_SCHED __builtin_amdgcn_sched_barrier(0)
; template <class Epi, class Sched, bool ALIGN_EPI = true>
; __device__ __forceinline__ void gemm_phase(LAS unsigned char* lds, const Gemm g, const Sched& S, const Epi& E) {
;     ...
;             const bool last = (t == nt - 2);
;             const char* a1 = cA + (size_t)(t + 1) * kstep;
;             const char* a2 = last ? nA : cA + (size_t)(t + 2) * kstep; const char* b2 = last ? nB : cB + (size_t)(t + 2) * kstep;
;             const char* a3 = a2 + kstep; const char* b3 = b2 + kstep;
;             PG8_LDB(B0, 0, 0); PG8_LDB(B1, 0, 1); PG8_SCHED; PG8_LDA(At, 0, 0); PG8_STAGE(PG8_SA(1, 1), a1 + hA, voffA);
;             PG8_WAIT_V(8); PG8_WAIT_L(0); PG8_BAR; PG8_MMA(0, 0, At, B0); PG8_MMA(0, 1, At, B1); PG8_BAR; PG8_SCHED;
;             PG8_LDA(At, 0, 1); PG8_STAGE(PG8_SB(0, 0), b2, voffB); PG8_STAGE(PG8_SB(0, 1), b2 + hB, voffB); PG8_STAGE(PG8_SA(0, 0), a2, voffA);
;             PG8_WAIT_V(8); PG8_WAIT_L(0); PG8_BAR; PG8_MMA(1, 0, At, B0); PG8_MMA(1, 1, At, B1); PG8_BAR; PG8_SCHED;
.LBB0_77:
	s_add_u32 s26, s6, 0xfff80080
	s_addc_u32 s27, s7, -1
	s_add_i32 s30, 0, 0x10000
	s_cmp_eq_u32 s25, 28
	s_cselect_b32 s45, s15, s27
	s_cselect_b32 s44, s17, s26
	s_cselect_b32 s43, s13, s24
	s_cselect_b32 s42, s18, s19
	s_add_i32 s31, 0, 0x14000
	v_add_u32_e32 v144, s30, v166
	v_add_u32_e32 v156, s31, v166
	ds_read_b128 v[132:135], v144
	ds_read_b128 v[136:139], v144 offset:1024
	ds_read_b128 v[140:143], v144 offset:2048
	ds_read_b128 v[144:147], v144 offset:3072
	ds_read_b128 v[170:173], v156
	ds_read_b128 v[174:177], v156 offset:1024
	ds_read_b128 v[178:181], v156 offset:2048
	ds_read_b128 v[182:185], v156 offset:3072
	v_lshl_add_u64 v[156:157], s[6:7], 0, v[152:153]
	s_add_i32 m0, s60, 0xc000
	ds_read_b128 v[186:189], v168
	ds_read_b128 v[190:193], v168 offset:1024
	ds_read_b128 v[194:197], v168 offset:2048
	ds_read_b128 v[204:207], v168 offset:3072
	ds_read_b128 v[208:211], v168 offset:4096
	ds_read_b128 v[212:215], v168 offset:5120
	ds_read_b128 v[216:219], v168 offset:6144
	ds_read_b128 v[220:223], v168 offset:7168
	global_load_lds_dwordx4 v[156:157], off
	v_lshl_add_u64 v[156:157], s[6:7], 0, v[154:155]
	s_add_i32 m0, s60, 0xe000
	s_nop 0
	global_load_lds_dwordx4 v[156:157], off
	s_waitcnt vmcnt(8)
	s_waitcnt lgkmcnt(0)
	s_barrier
	s_setprio 1
	s_waitcnt lgkmcnt(0)
	v_mfma_f32_16x16x32_bf16 v[128:131], v[132:135], v[186:189], v[128:131]
	v_mfma_f32_16x16x32_bf16 v[128:131], v[136:139], v[190:193], v[128:131]
	v_mfma_f32_16x16x32_bf16 v[124:127], v[140:143], v[186:189], v[124:127]
	v_mfma_f32_16x16x32_bf16 v[124:127], v[144:147], v[190:193], v[124:127]
	v_mfma_f32_16x16x32_bf16 v[116:119], v[132:135], v[194:197], v[116:119]
	v_mfma_f32_16x16x32_bf16 v[116:119], v[136:139], v[204:207], v[116:119]
	v_mfma_f32_16x16x32_bf16 v[112:115], v[140:143], v[194:197], v[112:115]
	v_mfma_f32_16x16x32_bf16 v[112:115], v[144:147], v[204:207], v[112:115]
	v_mfma_f32_16x16x32_bf16 v[104:107], v[132:135], v[208:211], v[104:107]
	v_mfma_f32_16x16x32_bf16 v[104:107], v[136:139], v[212:215], v[104:107]
	v_mfma_f32_16x16x32_bf16 v[96:99], v[140:143], v[208:211], v[96:99]
	v_mfma_f32_16x16x32_bf16 v[96:99], v[144:147], v[212:215], v[96:99]
	v_mfma_f32_16x16x32_bf16 v[88:91], v[132:135], v[216:219], v[88:91]
	v_mfma_f32_16x16x32_bf16 v[88:91], v[136:139], v[220:223], v[88:91]
	v_mfma_f32_16x16x32_bf16 v[80:83], v[140:143], v[216:219], v[80:83]
	v_mfma_f32_16x16x32_bf16 v[80:83], v[144:147], v[220:223], v[80:83]
	s_setprio 0
	s_setprio 1
	v_mfma_f32_16x16x32_bf16 v[120:123], v[170:173], v[186:189], v[120:123]
	v_mfma_f32_16x16x32_bf16 v[120:123], v[174:177], v[190:193], v[120:123]
	v_mfma_f32_16x16x32_bf16 v[108:111], v[178:181], v[186:189], v[108:111]
	v_mfma_f32_16x16x32_bf16 v[108:111], v[182:185], v[190:193], v[108:111]
	v_mfma_f32_16x16x32_bf16 v[100:103], v[170:173], v[194:197], v[100:103]
	v_mfma_f32_16x16x32_bf16 v[100:103], v[174:177], v[204:207], v[100:103]
	v_mfma_f32_16x16x32_bf16 v[92:95], v[178:181], v[194:197], v[92:95]
	v_mfma_f32_16x16x32_bf16 v[92:95], v[182:185], v[204:207], v[92:95]
	v_mfma_f32_16x16x32_bf16 v[84:87], v[170:173], v[208:211], v[84:87]
	v_mfma_f32_16x16x32_bf16 v[84:87], v[174:177], v[212:215], v[84:87]
	v_mfma_f32_16x16x32_bf16 v[76:79], v[178:181], v[208:211], v[76:79]
	v_mfma_f32_16x16x32_bf16 v[76:79], v[182:185], v[212:215], v[76:79]
	s_setprio 2
	s_barrier
	v_mfma_f32_16x16x32_bf16 v[72:75], v[170:173], v[216:219], v[72:75]
	v_mfma_f32_16x16x32_bf16 v[72:75], v[174:177], v[220:223], v[72:75]
	v_mfma_f32_16x16x32_bf16 v[68:71], v[178:181], v[216:219], v[68:71]
	v_mfma_f32_16x16x32_bf16 v[68:71], v[182:185], v[220:223], v[68:71]
	s_setprio 0
	s_add_i32 s26, s30, s59
	v_lshl_add_u64 v[156:157], s[42:43], 0, v[2:3]
	s_mov_b32 m0, s26
	ds_read_b128 v[186:189], v168 offset:16384
	ds_read_b128 v[190:193], v168 offset:17408
	ds_read_b128 v[194:197], v168 offset:18432
	ds_read_b128 v[204:207], v168 offset:19456
	ds_read_b128 v[208:211], v168 offset:20480
	ds_read_b128 v[212:215], v168 offset:21504
	ds_read_b128 v[216:219], v168 offset:22528
	ds_read_b128 v[220:223], v168 offset:23552
	global_load_lds_dwordx4 v[156:157], off
	s_add_i32 m0, s26, 0x2000
	s_add_u32 s26, s42, 0x80000
	v_lshl_add_u64 v[164:165], s[42:43], 0, v[0:1]
	s_addc_u32 s27, s43, 0
	s_add_i32 s30, s31, s59
	global_load_lds_dwordx4 v[164:165], off
	v_lshl_add_u64 v[224:225], s[26:27], 0, v[2:3]
	s_mov_b32 m0, s30
	v_lshl_add_u64 v[226:227], s[44:45], 0, v[148:149]
	global_load_lds_dwordx4 v[224:225], off
	v_lshl_add_u64 v[224:225], s[26:27], 0, v[0:1]
	s_add_i32 m0, s30, 0x2000
	s_nop 0
	global_load_lds_dwordx4 v[224:225], off
	v_lshl_add_u64 v[224:225], s[44:45], 0, v[150:151]
	s_mov_b32 m0, s60
	s_nop 0
	global_load_lds_dwordx4 v[224:225], off
	s_mov_b32 m0, s61
	s_nop 0
	global_load_lds_dwordx4 v[226:227], off
	s_waitcnt vmcnt(8)
	s_waitcnt lgkmcnt(0)
	s_barrier
; #define PG8_STAGE(bufoff, gbase, voff) do { _Pragma("unroll") for (int _i = 0; _i < 2; ++_i) \
;         __builtin_amdgcn_global_load_lds((const unsigned*)((const char*)(gbase) + (voff)[_i]), (LAS unsigned*)(lds + (bufoff) + ldsw + _i * 8192), 16, 0, 0); } while (0)
; #define PG8_LDA(dst, b, h) do { _Pragma("unroll") for (int m = 0; m < 4; ++m) _Pragma("unroll") for (int k = 0; k < 2; ++k) dst[m][k] = *(const LAS bf16x8*)(lds + PG8_SA(b, h) + aoff + m * 2048 + k * 1024); } while (0)
; #define PG8_LDB(dst, b, h) do { _Pragma("unroll") for (int n = 0; n < 2; ++n) _Pragma("unroll") for (int k = 0; k < 2; ++k) dst[n][k] = *(const LAS bf16x8*)(lds + PG8_SB(b, h) + boff + n * 2048 + k * 1024); } while (0)
; #define PG8_MMA(ai, bj, At, Bt) do { __builtin_amdgcn_s_setprio(1); _Pragma("unroll") for (int m = 0; m < 4; ++m) _Pragma("unroll") for (int n = 0; n < 2; ++n) _Pragma("unroll") for (int k = 0; k < 2; ++k) \
;         acc[ai][bj][m][n] = __builtin_amdgcn_mfma_f32_16x16x32_bf16(Bt[n][k], At[m][k], acc[ai][bj][m][n], 0, 0, 0); __builtin_amdgcn_s_setprio(0); } while (0)
; #define PG8_WAIT_V(n) asm volatile("s_waitcnt vmcnt(" #n ")" ::: "memory")
; #define PG8_WAIT_L(n) asm volatile("s_waitcnt lgkmcnt(" #n ")" ::: "memory")
; #define PG8_BAR __builtin_amdgcn_s_barrier()
; #define PG8_SCHED __builtin_amdgcn_sched_barrier(0)
; template <class Epi, class Sched, bool ALIGN_EPI = true>
; __device__ __forceinline__ void gemm_phase(LAS unsigned char* lds, const Gemm g, const Sched& S, const Epi& E) {
;     ...
;             PG8_WAIT_V(8); PG8_WAIT_L(0); PG8_BAR; PG8_MMA(1, 0, At, B0); PG8_MMA(1, 1, At, B1); PG8_BAR; PG8_SCHED;
;             PG8_LDB(B0, 1, 0); PG8_LDB(B1, 1, 1); PG8_SCHED; PG8_LDA(At, 1, 0); PG8_STAGE(PG8_SA(0, 1), a2 + hA, voffA);
;             PG8_WAIT_V(8); PG8_WAIT_L(0); PG8_BAR; PG8_MMA(0, 0, At, B0); PG8_MMA(0, 1, At, B1); PG8_BAR; PG8_SCHED;
	s_setprio 1
	s_waitcnt lgkmcnt(0)
	v_mfma_f32_16x16x32_bf16 v[64:67], v[132:135], v[186:189], v[64:67]
	v_mfma_f32_16x16x32_bf16 v[64:67], v[136:139], v[190:193], v[64:67]
	v_mfma_f32_16x16x32_bf16 v[60:63], v[140:143], v[186:189], v[60:63]
	v_mfma_f32_16x16x32_bf16 v[60:63], v[144:147], v[190:193], v[60:63]
	v_mfma_f32_16x16x32_bf16 v[56:59], v[132:135], v[194:197], v[56:59]
	v_mfma_f32_16x16x32_bf16 v[56:59], v[136:139], v[204:207], v[56:59]
	v_mfma_f32_16x16x32_bf16 v[48:51], v[140:143], v[194:197], v[48:51]
	v_mfma_f32_16x16x32_bf16 v[48:51], v[144:147], v[204:207], v[48:51]
	v_mfma_f32_16x16x32_bf16 v[40:43], v[132:135], v[208:211], v[40:43]
	v_mfma_f32_16x16x32_bf16 v[40:43], v[136:139], v[212:215], v[40:43]
	v_mfma_f32_16x16x32_bf16 v[32:35], v[140:143], v[208:211], v[32:35]
	v_mfma_f32_16x16x32_bf16 v[32:35], v[144:147], v[212:215], v[32:35]
	v_mfma_f32_16x16x32_bf16 v[24:27], v[132:135], v[216:219], v[24:27]
	v_mfma_f32_16x16x32_bf16 v[24:27], v[136:139], v[220:223], v[24:27]
	v_mfma_f32_16x16x32_bf16 v[16:19], v[140:143], v[216:219], v[16:19]
	v_mfma_f32_16x16x32_bf16 v[16:19], v[144:147], v[220:223], v[16:19]
	s_setprio 0
	s_setprio 1
	v_mfma_f32_16x16x32_bf16 v[52:55], v[170:173], v[186:189], v[52:55]
	v_mfma_f32_16x16x32_bf16 v[52:55], v[174:177], v[190:193], v[52:55]
	v_mfma_f32_16x16x32_bf16 v[44:47], v[178:181], v[186:189], v[44:47]
	v_mfma_f32_16x16x32_bf16 v[44:47], v[182:185], v[190:193], v[44:47]
	v_mfma_f32_16x16x32_bf16 v[36:39], v[170:173], v[194:197], v[36:39]
	v_mfma_f32_16x16x32_bf16 v[36:39], v[174:177], v[204:207], v[36:39]
	v_mfma_f32_16x16x32_bf16 v[28:31], v[178:181], v[194:197], v[28:31]
	v_mfma_f32_16x16x32_bf16 v[28:31], v[182:185], v[204:207], v[28:31]
	v_mfma_f32_16x16x32_bf16 v[20:23], v[170:173], v[208:211], v[20:23]
	v_mfma_f32_16x16x32_bf16 v[20:23], v[174:177], v[212:215], v[20:23]
	v_mfma_f32_16x16x32_bf16 v[12:15], v[178:181], v[208:211], v[12:15]
	v_mfma_f32_16x16x32_bf16 v[12:15], v[182:185], v[212:215], v[12:15]
	s_setprio 2
	s_barrier
	v_mfma_f32_16x16x32_bf16 v[8:11], v[170:173], v[216:219], v[8:11]
	v_mfma_f32_16x16x32_bf16 v[8:11], v[174:177], v[220:223], v[8:11]
	v_mfma_f32_16x16x32_bf16 v[4:7], v[178:181], v[216:219], v[4:7]
	v_mfma_f32_16x16x32_bf16 v[4:7], v[182:185], v[220:223], v[4:7]
	s_setprio 0
	s_add_i32 s30, 0, 0x18000
	s_add_i32 s31, 0, 0x1c000
	v_add_u32_e32 v144, s30, v166
	v_add_u32_e32 v160, s31, v166
	ds_read_b128 v[132:135], v144
	ds_read_b128 v[136:139], v144 offset:1024
	ds_read_b128 v[140:143], v144 offset:2048
	ds_read_b128 v[144:147], v144 offset:3072
	ds_read_b128 v[170:173], v160
	ds_read_b128 v[174:177], v160 offset:1024
	ds_read_b128 v[178:181], v160 offset:2048
	ds_read_b128 v[182:185], v160 offset:3072
	s_add_u32 s26, s44, 0x80000
	s_addc_u32 s27, s45, 0
	s_mov_b32 m0, s62
	v_lshl_add_u64 v[228:229], s[26:27], 0, v[150:151]
	ds_read_b128 v[186:189], v168 offset:32768
	ds_read_b128 v[190:193], v168 offset:33792
	ds_read_b128 v[194:197], v168 offset:34816
	ds_read_b128 v[204:207], v168 offset:35840
	ds_read_b128 v[208:211], v168 offset:36864
	ds_read_b128 v[212:215], v168 offset:37888
	ds_read_b128 v[216:219], v168 offset:38912
	ds_read_b128 v[220:223], v168 offset:39936
	global_load_lds_dwordx4 v[228:229], off
	v_lshl_add_u64 v[228:229], s[26:27], 0, v[148:149]
	s_mov_b32 m0, s63
	s_nop 0
	global_load_lds_dwordx4 v[228:229], off
	s_waitcnt vmcnt(8)
	s_waitcnt lgkmcnt(0)
	s_barrier
	s_setprio 1
	s_waitcnt lgkmcnt(0)
	v_mfma_f32_16x16x32_bf16 v[128:131], v[132:135], v[186:189], v[128:131]
	v_mfma_f32_16x16x32_bf16 v[128:131], v[136:139], v[190:193], v[128:131]
	v_mfma_f32_16x16x32_bf16 v[124:127], v[140:143], v[186:189], v[124:127]
	v_mfma_f32_16x16x32_bf16 v[124:127], v[144:147], v[190:193], v[124:127]
	v_mfma_f32_16x16x32_bf16 v[116:119], v[132:135], v[194:197], v[116:119]
	v_mfma_f32_16x16x32_bf16 v[116:119], v[136:139], v[204:207], v[116:119]
	v_mfma_f32_16x16x32_bf16 v[112:115], v[140:143], v[194:197], v[112:115]
	v_mfma_f32_16x16x32_bf16 v[112:115], v[144:147], v[204:207], v[112:115]
	v_mfma_f32_16x16x32_bf16 v[104:107], v[132:135], v[208:211], v[104:107]
	v_mfma_f32_16x16x32_bf16 v[104:107], v[136:139], v[212:215], v[104:107]
	v_mfma_f32_16x16x32_bf16 v[96:99], v[140:143], v[208:211], v[96:99]
	v_mfma_f32_16x16x32_bf16 v[96:99], v[144:147], v[212:215], v[96:99]
	v_mfma_f32_16x16x32_bf16 v[88:91], v[132:135], v[216:219], v[88:91]
	v_mfma_f32_16x16x32_bf16 v[88:91], v[136:139], v[220:223], v[88:91]
	v_mfma_f32_16x16x32_bf16 v[80:83], v[140:143], v[216:219], v[80:83]
	v_mfma_f32_16x16x32_bf16 v[80:83], v[144:147], v[220:223], v[80:83]
	s_setprio 0
	s_setprio 1
	v_mfma_f32_16x16x32_bf16 v[120:123], v[170:173], v[186:189], v[120:123]
	v_mfma_f32_16x16x32_bf16 v[120:123], v[174:177], v[190:193], v[120:123]
	v_mfma_f32_16x16x32_bf16 v[108:111], v[178:181], v[186:189], v[108:111]
	v_mfma_f32_16x16x32_bf16 v[108:111], v[182:185], v[190:193], v[108:111]
	v_mfma_f32_16x16x32_bf16 v[100:103], v[170:173], v[194:197], v[100:103]
	v_mfma_f32_16x16x32_bf16 v[100:103], v[174:177], v[204:207], v[100:103]
	v_mfma_f32_16x16x32_bf16 v[92:95], v[178:181], v[194:197], v[92:95]
	v_mfma_f32_16x16x32_bf16 v[92:95], v[182:185], v[204:207], v[92:95]
	v_mfma_f32_16x16x32_bf16 v[84:87], v[170:173], v[208:211], v[84:87]
	v_mfma_f32_16x16x32_bf16 v[84:87], v[174:177], v[212:215], v[84:87]
	v_mfma_f32_16x16x32_bf16 v[76:79], v[178:181], v[208:211], v[76:79]
	v_mfma_f32_16x16x32_bf16 v[76:79], v[182:185], v[212:215], v[76:79]
	s_setprio 2
	s_barrier
; #define PG8_STAGE(bufoff, gbase, voff) do { _Pragma("unroll") for (int _i = 0; _i < 2; ++_i) \
;         __builtin_amdgcn_global_load_lds((const unsigned*)((const char*)(gbase) + (voff)[_i]), (LAS unsigned*)(lds + (bufoff) + ldsw + _i * 8192), 16, 0, 0); } while (0)
; #define PG8_LDA(dst, b, h) do { _Pragma("unroll") for (int m = 0; m < 4; ++m) _Pragma("unroll") for (int k = 0; k < 2; ++k) dst[m][k] = *(const LAS bf16x8*)(lds + PG8_SA(b, h) + aoff + m * 2048 + k * 1024); } while (0)
; #define PG8_MMA(ai, bj, At, Bt) do { __builtin_amdgcn_s_setprio(1); _Pragma("unroll") for (int m = 0; m < 4; ++m) _Pragma("unroll") for (int n = 0; n < 2; ++n) _Pragma("unroll") for (int k = 0; k < 2; ++k) \
;         acc[ai][bj][m][n] = __builtin_amdgcn_mfma_f32_16x16x32_bf16(Bt[n][k], At[m][k], acc[ai][bj][m][n], 0, 0, 0); __builtin_amdgcn_s_setprio(0); } while (0)
; #define PG8_WAIT_V(n) asm volatile("s_waitcnt vmcnt(" #n ")" ::: "memory")
; #define PG8_WAIT_L(n) asm volatile("s_waitcnt lgkmcnt(" #n ")" ::: "memory")
; #define PG8_BAR __builtin_amdgcn_s_barrier()
; #define PG8_SCHED __builtin_amdgcn_sched_barrier(0)
; template <class Epi, class Sched, bool ALIGN_EPI = true>
; __device__ __forceinline__ void gemm_phase(LAS unsigned char* lds, const Gemm g, const Sched& S, const Epi& E) {
;     ...
;             PG8_WAIT_V(8); PG8_WAIT_L(0); PG8_BAR; PG8_MMA(0, 0, At, B0); PG8_MMA(0, 1, At, B1); PG8_BAR; PG8_SCHED;
;             PG8_LDA(At, 1, 1); PG8_STAGE(PG8_SB(1, 0), b3, voffB); PG8_STAGE(PG8_SB(1, 1), b3 + hB, voffB); PG8_STAGE(PG8_SA(1, 0), a3, voffA);
;             PG8_WAIT_V(8); PG8_WAIT_L(0); PG8_BAR; PG8_MMA(1, 0, At, B0); PG8_MMA(1, 1, At, B1); PG8_BAR; PG8_SCHED;
;         }
;         if constexpr (ALIGN_EPI) { if (wr == 0) PG8_BAR; }
	v_mfma_f32_16x16x32_bf16 v[72:75], v[170:173], v[216:219], v[72:75]
	v_mfma_f32_16x16x32_bf16 v[72:75], v[174:177], v[220:223], v[72:75]
	v_mfma_f32_16x16x32_bf16 v[68:71], v[178:181], v[216:219], v[68:71]
	v_mfma_f32_16x16x32_bf16 v[68:71], v[182:185], v[220:223], v[68:71]
	s_setprio 0
	s_add_i32 s26, s30, s59
	v_lshl_add_u64 v[156:157], v[156:157], 0, s[86:87]
	s_mov_b32 m0, s26
	ds_read_b128 v[186:189], v168 offset:49152
	ds_read_b128 v[190:193], v168 offset:50176
	ds_read_b128 v[194:197], v168 offset:51200
	ds_read_b128 v[204:207], v168 offset:52224
	ds_read_b128 v[208:211], v168 offset:53248
	ds_read_b128 v[212:215], v168 offset:54272
	ds_read_b128 v[216:219], v168 offset:55296
	ds_read_b128 v[220:223], v168 offset:56320
	global_load_lds_dwordx4 v[156:157], off
	s_add_i32 m0, s26, 0x2000
	s_add_u32 s26, s42, 0x80080
	v_lshl_add_u64 v[156:157], v[164:165], 0, s[86:87]
	s_addc_u32 s27, s43, 0
	s_add_i32 s30, s31, s59
	global_load_lds_dwordx4 v[156:157], off
	v_lshl_add_u64 v[156:157], s[26:27], 0, v[2:3]
	s_mov_b32 m0, s30
	s_nop 0
	global_load_lds_dwordx4 v[156:157], off
	v_lshl_add_u64 v[156:157], s[26:27], 0, v[0:1]
	s_add_i32 m0, s30, 0x2000
	s_nop 0
	global_load_lds_dwordx4 v[156:157], off
	v_lshl_add_u64 v[156:157], v[224:225], 0, s[86:87]
	s_mov_b32 m0, s64
	s_nop 0
	global_load_lds_dwordx4 v[156:157], off
	v_lshl_add_u64 v[156:157], v[226:227], 0, s[86:87]
	s_mov_b32 m0, s65
	s_nop 0
	global_load_lds_dwordx4 v[156:157], off
	s_waitcnt vmcnt(8)
	s_waitcnt lgkmcnt(0)
	s_barrier
	s_setprio 1
	s_waitcnt lgkmcnt(0)
	v_mfma_f32_16x16x32_bf16 v[64:67], v[132:135], v[186:189], v[64:67]
	v_mfma_f32_16x16x32_bf16 v[64:67], v[136:139], v[190:193], v[64:67]
	v_mfma_f32_16x16x32_bf16 v[60:63], v[140:143], v[186:189], v[60:63]
	v_mfma_f32_16x16x32_bf16 v[60:63], v[144:147], v[190:193], v[60:63]
	v_mfma_f32_16x16x32_bf16 v[56:59], v[132:135], v[194:197], v[56:59]
	v_mfma_f32_16x16x32_bf16 v[56:59], v[136:139], v[204:207], v[56:59]
	v_mfma_f32_16x16x32_bf16 v[48:51], v[140:143], v[194:197], v[48:51]
	v_mfma_f32_16x16x32_bf16 v[48:51], v[144:147], v[204:207], v[48:51]
	v_mfma_f32_16x16x32_bf16 v[40:43], v[132:135], v[208:211], v[40:43]
	v_mfma_f32_16x16x32_bf16 v[40:43], v[136:139], v[212:215], v[40:43]
	v_mfma_f32_16x16x32_bf16 v[32:35], v[140:143], v[208:211], v[32:35]
	v_mfma_f32_16x16x32_bf16 v[32:35], v[144:147], v[212:215], v[32:35]
	v_mfma_f32_16x16x32_bf16 v[24:27], v[132:135], v[216:219], v[24:27]
	v_mfma_f32_16x16x32_bf16 v[24:27], v[136:139], v[220:223], v[24:27]
	v_mfma_f32_16x16x32_bf16 v[16:19], v[140:143], v[216:219], v[16:19]
	v_mfma_f32_16x16x32_bf16 v[16:19], v[144:147], v[220:223], v[16:19]
	s_setprio 0
	s_setprio 1
	v_mfma_f32_16x16x32_bf16 v[52:55], v[170:173], v[186:189], v[52:55]
	v_mfma_f32_16x16x32_bf16 v[52:55], v[174:177], v[190:193], v[52:55]
	v_mfma_f32_16x16x32_bf16 v[44:47], v[178:181], v[186:189], v[44:47]
	v_mfma_f32_16x16x32_bf16 v[44:47], v[182:185], v[190:193], v[44:47]
	v_mfma_f32_16x16x32_bf16 v[36:39], v[170:173], v[194:197], v[36:39]
	v_mfma_f32_16x16x32_bf16 v[36:39], v[174:177], v[204:207], v[36:39]
	v_mfma_f32_16x16x32_bf16 v[28:31], v[178:181], v[194:197], v[28:31]
	v_mfma_f32_16x16x32_bf16 v[28:31], v[182:185], v[204:207], v[28:31]
	v_mfma_f32_16x16x32_bf16 v[20:23], v[170:173], v[208:211], v[20:23]
	v_mfma_f32_16x16x32_bf16 v[20:23], v[174:177], v[212:215], v[20:23]
	v_mfma_f32_16x16x32_bf16 v[12:15], v[178:181], v[208:211], v[12:15]
	v_mfma_f32_16x16x32_bf16 v[12:15], v[182:185], v[212:215], v[12:15]
	s_setprio 2
	s_barrier
	v_mfma_f32_16x16x32_bf16 v[8:11], v[170:173], v[216:219], v[8:11]
	v_mfma_f32_16x16x32_bf16 v[8:11], v[174:177], v[220:223], v[8:11]
	v_mfma_f32_16x16x32_bf16 v[4:7], v[178:181], v[216:219], v[4:7]
	v_mfma_f32_16x16x32_bf16 v[4:7], v[182:185], v[220:223], v[4:7]
	s_setprio 0
	s_add_i32 s25, s25, 2
	s_add_u32 s6, s6, 0x100
	s_addc_u32 s7, s7, 0
	s_add_u32 s19, s19, 0x100
	s_addc_u32 s24, s24, 0
	s_cmp_gt_u32 s25, 29
	s_cbranch_scc0 .LBB0_77
	s_and_b64 vcc, exec, s[10:11]
	s_cbranch_vccz .LBB0_80
	s_barrier

; #define PG8_STAGE(bufoff, gbase, voff) do { _Pragma("unroll") for (int _i = 0; _i < 2; ++_i) \
;         __builtin_amdgcn_global_load_lds((const unsigned*)((const char*)(gbase) + (voff)[_i]), (LAS unsigned*)(lds + (bufoff) + ldsw + _i * 8192), 16, 0, 0); } while (0)
; #define PG8_LDA(dst, b, h) do { _Pragma("unroll") for (int m = 0; m < 4; ++m) _Pragma("unroll") for (int k = 0; k < 2; ++k) dst[m][k] = *(const LAS bf16x8*)(lds + PG8_SA(b, h) + aoff + m * 2048 + k * 1024); } while (0)
; #define PG8_LDB(dst, b, h) do { _Pragma("unroll") for (int n = 0; n < 2; ++n) _Pragma("unroll") for (int k = 0; k < 2; ++k) dst[n][k] = *(const LAS bf16x8*)(lds + PG8_SB(b, h) + boff + n * 2048 + k * 1024); } while (0)
; #define PG8_MMA(ai, bj, At, Bt) do { __builtin_amdgcn_s_setprio(1); _Pragma("unroll") for (int m = 0; m < 4; ++m) _Pragma("unroll") for (int n = 0; n < 2; ++n) _Pragma("unroll") for (int k = 0; k < 2; ++k) \
;         acc[ai][bj][m][n] = __builtin_amdgcn_mfma_f32_16x16x32_bf16(Bt[n][k], At[m][k], acc[ai][bj][m][n], 0, 0, 0); __builtin_amdgcn_s_setprio(0); } while (0)
; #define PG8_WAIT_V(n) asm volatile("s_waitcnt vmcnt(" #n ")" ::: "memory")
; #define PG8_WAIT_L(n) asm volatile("s_waitcnt lgkmcnt(" #n ")" ::: "memory")
; #define PG8_BAR __builtin_amdgcn_s_barrier()
; #define PG8_SCHED __builtin_amdgcn_sched_barrier(0)
; template <class Epi, class Sched, bool ALIGN_EPI = true>
; __device__ __forceinline__ void gemm_phase(LAS unsigned char* lds, const Gemm g, const Sched& S, const Epi& E) {
;     ...
;             const bool last = (t == nt - 2);
;             const char* a1 = cA + (size_t)(t + 1) * kstep;
;             const char* a2 = last ? nA : cA + (size_t)(t + 2) * kstep; const char* b2 = last ? nB : cB + (size_t)(t + 2) * kstep;
;             const char* a3 = a2 + kstep; const char* b3 = b2 + kstep;
;             PG8_LDB(B0, 0, 0); PG8_LDB(B1, 0, 1); PG8_SCHED; PG8_LDA(At, 0, 0); PG8_STAGE(PG8_SA(1, 1), a1 + hA, voffA);
;             PG8_WAIT_V(8); PG8_WAIT_L(0); PG8_BAR; PG8_MMA(0, 0, At, B0); PG8_MMA(0, 1, At, B1); PG8_BAR; PG8_SCHED;
;             PG8_LDA(At, 0, 1); PG8_STAGE(PG8_SB(0, 0), b2, voffB); PG8_STAGE(PG8_SB(0, 1), b2 + hB, voffB); PG8_STAGE(PG8_SA(0, 0), a2, voffA);
;             PG8_WAIT_V(8); PG8_WAIT_L(0); PG8_BAR; PG8_MMA(1, 0, At, B0); PG8_MMA(1, 1, At, B1); PG8_BAR; PG8_SCHED;
.LBB0_218:
	s_add_u32 s27, s38, 0xfff80080
	s_addc_u32 s30, s39, -1
	s_add_i32 s31, 0, 0x10000
	s_cmp_eq_u32 s26, 28
	s_cselect_b32 s43, s11, s30
	s_cselect_b32 s42, s18, s27
	v_add_u32_e32 v156, s31, v145
	s_cselect_b32 s41, s9, s25
	s_cselect_b32 s40, s19, s24
	s_add_i32 s27, 0, 0x14000
	ds_read_b128 v[140:143], v156
	ds_read_b128 v[148:151], v156 offset:1024
	ds_read_b128 v[152:155], v156 offset:2048
	ds_read_b128 v[164:167], v156 offset:3072
	v_add_u32_e32 v156, s27, v145
	ds_read_b128 v[168:171], v156
	ds_read_b128 v[172:175], v156 offset:1024
	ds_read_b128 v[176:179], v156 offset:2048
	ds_read_b128 v[180:183], v156 offset:3072
	v_lshl_add_u64 v[156:157], s[38:39], 0, v[136:137]
	s_add_i32 m0, s58, 0xc000
	ds_read_b128 v[184:187], v147
	ds_read_b128 v[188:191], v147 offset:1024
	ds_read_b128 v[192:195], v147 offset:2048
	ds_read_b128 v[204:207], v147 offset:3072
	ds_read_b128 v[208:211], v147 offset:4096
	ds_read_b128 v[212:215], v147 offset:5120
	ds_read_b128 v[216:219], v147 offset:6144
	ds_read_b128 v[220:223], v147 offset:7168
	global_load_lds_dwordx4 v[156:157], off
	v_lshl_add_u64 v[156:157], s[38:39], 0, v[138:139]
	s_add_i32 m0, s58, 0xe000
	s_nop 0
	global_load_lds_dwordx4 v[156:157], off
	s_waitcnt vmcnt(8)
	s_waitcnt lgkmcnt(0)
	s_barrier
	s_setprio 1
	s_waitcnt lgkmcnt(0)
	v_mfma_f32_16x16x32_bf16 v[128:131], v[140:143], v[184:187], v[128:131]
	v_mfma_f32_16x16x32_bf16 v[128:131], v[148:151], v[188:191], v[128:131]
	v_mfma_f32_16x16x32_bf16 v[124:127], v[152:155], v[184:187], v[124:127]
	v_mfma_f32_16x16x32_bf16 v[124:127], v[164:167], v[188:191], v[124:127]
	v_mfma_f32_16x16x32_bf16 v[120:123], v[140:143], v[192:195], v[120:123]
	v_mfma_f32_16x16x32_bf16 v[120:123], v[148:151], v[204:207], v[120:123]
	v_mfma_f32_16x16x32_bf16 v[112:115], v[152:155], v[192:195], v[112:115]
	v_mfma_f32_16x16x32_bf16 v[112:115], v[164:167], v[204:207], v[112:115]
	v_mfma_f32_16x16x32_bf16 v[104:107], v[140:143], v[208:211], v[104:107]
	v_mfma_f32_16x16x32_bf16 v[104:107], v[148:151], v[212:215], v[104:107]
	v_mfma_f32_16x16x32_bf16 v[96:99], v[152:155], v[208:211], v[96:99]
	v_mfma_f32_16x16x32_bf16 v[96:99], v[164:167], v[212:215], v[96:99]
	v_mfma_f32_16x16x32_bf16 v[88:91], v[140:143], v[216:219], v[88:91]
	v_mfma_f32_16x16x32_bf16 v[88:91], v[148:151], v[220:223], v[88:91]
	v_mfma_f32_16x16x32_bf16 v[80:83], v[152:155], v[216:219], v[80:83]
	v_mfma_f32_16x16x32_bf16 v[80:83], v[164:167], v[220:223], v[80:83]
	s_setprio 0
	s_setprio 1
	v_mfma_f32_16x16x32_bf16 v[116:119], v[168:171], v[184:187], v[116:119]
	v_mfma_f32_16x16x32_bf16 v[116:119], v[172:175], v[188:191], v[116:119]
	v_mfma_f32_16x16x32_bf16 v[108:111], v[176:179], v[184:187], v[108:111]
	v_mfma_f32_16x16x32_bf16 v[108:111], v[180:183], v[188:191], v[108:111]
	v_mfma_f32_16x16x32_bf16 v[100:103], v[168:171], v[192:195], v[100:103]
	v_mfma_f32_16x16x32_bf16 v[100:103], v[172:175], v[204:207], v[100:103]
	v_mfma_f32_16x16x32_bf16 v[92:95], v[176:179], v[192:195], v[92:95]
	v_mfma_f32_16x16x32_bf16 v[92:95], v[180:183], v[204:207], v[92:95]
	v_mfma_f32_16x16x32_bf16 v[84:87], v[168:171], v[208:211], v[84:87]
	v_mfma_f32_16x16x32_bf16 v[84:87], v[172:175], v[212:215], v[84:87]
	v_mfma_f32_16x16x32_bf16 v[76:79], v[176:179], v[208:211], v[76:79]
	v_mfma_f32_16x16x32_bf16 v[76:79], v[180:183], v[212:215], v[76:79]
	s_setprio 2
	s_barrier
	v_mfma_f32_16x16x32_bf16 v[72:75], v[168:171], v[216:219], v[72:75]
	v_mfma_f32_16x16x32_bf16 v[72:75], v[172:175], v[220:223], v[72:75]
	v_mfma_f32_16x16x32_bf16 v[68:71], v[176:179], v[216:219], v[68:71]
	v_mfma_f32_16x16x32_bf16 v[68:71], v[180:183], v[220:223], v[68:71]
	s_setprio 0
	s_add_i32 s30, s31, s53
	v_lshl_add_u64 v[156:157], s[40:41], 0, v[2:3]
	s_mov_b32 m0, s30
	ds_read_b128 v[184:187], v147 offset:16384
	ds_read_b128 v[188:191], v147 offset:17408
	ds_read_b128 v[192:195], v147 offset:18432
	ds_read_b128 v[204:207], v147 offset:19456
	ds_read_b128 v[208:211], v147 offset:20480
	ds_read_b128 v[212:215], v147 offset:21504
	ds_read_b128 v[216:219], v147 offset:22528
	ds_read_b128 v[220:223], v147 offset:23552
	global_load_lds_dwordx4 v[156:157], off
	s_add_i32 m0, s30, 0x2000
	s_add_u32 s30, s40, 0x80000
	v_lshl_add_u64 v[196:197], s[40:41], 0, v[0:1]
	s_addc_u32 s31, s41, 0
	s_add_i32 s27, s27, s53
	global_load_lds_dwordx4 v[196:197], off
	v_lshl_add_u64 v[224:225], s[30:31], 0, v[2:3]
	s_mov_b32 m0, s27
	v_lshl_add_u64 v[226:227], s[42:43], 0, v[132:133]
	global_load_lds_dwordx4 v[224:225], off
	v_lshl_add_u64 v[224:225], s[30:31], 0, v[0:1]
	s_add_i32 m0, s27, 0x2000
	s_nop 0
	global_load_lds_dwordx4 v[224:225], off
	v_lshl_add_u64 v[224:225], s[42:43], 0, v[134:135]
	s_mov_b32 m0, s58
	s_nop 0
	global_load_lds_dwordx4 v[224:225], off
	s_mov_b32 m0, s59
	s_nop 0
	global_load_lds_dwordx4 v[226:227], off
	s_waitcnt vmcnt(8)
	s_waitcnt lgkmcnt(0)
	s_barrier
; #define PG8_STAGE(bufoff, gbase, voff) do { _Pragma("unroll") for (int _i = 0; _i < 2; ++_i) \
;         __builtin_amdgcn_global_load_lds((const unsigned*)((const char*)(gbase) + (voff)[_i]), (LAS unsigned*)(lds + (bufoff) + ldsw + _i * 8192), 16, 0, 0); } while (0)
; #define PG8_LDA(dst, b, h) do { _Pragma("unroll") for (int m = 0; m < 4; ++m) _Pragma("unroll") for (int k = 0; k < 2; ++k) dst[m][k] = *(const LAS bf16x8*)(lds + PG8_SA(b, h) + aoff + m * 2048 + k * 1024); } while (0)
; #define PG8_LDB(dst, b, h) do { _Pragma("unroll") for (int n = 0; n < 2; ++n) _Pragma("unroll") for (int k = 0; k < 2; ++k) dst[n][k] = *(const LAS bf16x8*)(lds + PG8_SB(b, h) + boff + n * 2048 + k * 1024); } while (0)
; #define PG8_MMA(ai, bj, At, Bt) do { __builtin_amdgcn_s_setprio(1); _Pragma("unroll") for (int m = 0; m < 4; ++m) _Pragma("unroll") for (int n = 0; n < 2; ++n) _Pragma("unroll") for (int k = 0; k < 2; ++k) \
;         acc[ai][bj][m][n] = __builtin_amdgcn_mfma_f32_16x16x32_bf16(Bt[n][k], At[m][k], acc[ai][bj][m][n], 0, 0, 0); __builtin_amdgcn_s_setprio(0); } while (0)
; #define PG8_WAIT_V(n) asm volatile("s_waitcnt vmcnt(" #n ")" ::: "memory")
; #define PG8_WAIT_L(n) asm volatile("s_waitcnt lgkmcnt(" #n ")" ::: "memory")
; #define PG8_BAR __builtin_amdgcn_s_barrier()
; #define PG8_SCHED __builtin_amdgcn_sched_barrier(0)
; template <class Epi, class Sched, bool ALIGN_EPI = true>
; __device__ __forceinline__ void gemm_phase(LAS unsigned char* lds, const Gemm g, const Sched& S, const Epi& E) {
;     ...
;             PG8_WAIT_V(8); PG8_WAIT_L(0); PG8_BAR; PG8_MMA(1, 0, At, B0); PG8_MMA(1, 1, At, B1); PG8_BAR; PG8_SCHED;
;             PG8_LDB(B0, 1, 0); PG8_LDB(B1, 1, 1); PG8_SCHED; PG8_LDA(At, 1, 0); PG8_STAGE(PG8_SA(0, 1), a2 + hA, voffA);
;             PG8_WAIT_V(8); PG8_WAIT_L(0); PG8_BAR; PG8_MMA(0, 0, At, B0); PG8_MMA(0, 1, At, B1); PG8_BAR; PG8_SCHED;
	s_setprio 1
	s_waitcnt lgkmcnt(0)
	v_mfma_f32_16x16x32_bf16 v[64:67], v[140:143], v[184:187], v[64:67]
	v_mfma_f32_16x16x32_bf16 v[64:67], v[148:151], v[188:191], v[64:67]
	v_mfma_f32_16x16x32_bf16 v[60:63], v[152:155], v[184:187], v[60:63]
	v_mfma_f32_16x16x32_bf16 v[60:63], v[164:167], v[188:191], v[60:63]
	v_mfma_f32_16x16x32_bf16 v[56:59], v[140:143], v[192:195], v[56:59]
	v_mfma_f32_16x16x32_bf16 v[56:59], v[148:151], v[204:207], v[56:59]
	v_mfma_f32_16x16x32_bf16 v[48:51], v[152:155], v[192:195], v[48:51]
	v_mfma_f32_16x16x32_bf16 v[48:51], v[164:167], v[204:207], v[48:51]
	v_mfma_f32_16x16x32_bf16 v[40:43], v[140:143], v[208:211], v[40:43]
	v_mfma_f32_16x16x32_bf16 v[40:43], v[148:151], v[212:215], v[40:43]
	v_mfma_f32_16x16x32_bf16 v[32:35], v[152:155], v[208:211], v[32:35]
	v_mfma_f32_16x16x32_bf16 v[32:35], v[164:167], v[212:215], v[32:35]
	v_mfma_f32_16x16x32_bf16 v[24:27], v[140:143], v[216:219], v[24:27]
	v_mfma_f32_16x16x32_bf16 v[24:27], v[148:151], v[220:223], v[24:27]
	v_mfma_f32_16x16x32_bf16 v[16:19], v[152:155], v[216:219], v[16:19]
	v_mfma_f32_16x16x32_bf16 v[16:19], v[164:167], v[220:223], v[16:19]
	s_setprio 0
	s_setprio 1
	v_mfma_f32_16x16x32_bf16 v[52:55], v[168:171], v[184:187], v[52:55]
	v_mfma_f32_16x16x32_bf16 v[52:55], v[172:175], v[188:191], v[52:55]
	v_mfma_f32_16x16x32_bf16 v[44:47], v[176:179], v[184:187], v[44:47]
	v_mfma_f32_16x16x32_bf16 v[44:47], v[180:183], v[188:191], v[44:47]
	v_mfma_f32_16x16x32_bf16 v[36:39], v[168:171], v[192:195], v[36:39]
	v_mfma_f32_16x16x32_bf16 v[36:39], v[172:175], v[204:207], v[36:39]
	v_mfma_f32_16x16x32_bf16 v[28:31], v[176:179], v[192:195], v[28:31]
	v_mfma_f32_16x16x32_bf16 v[28:31], v[180:183], v[204:207], v[28:31]
	v_mfma_f32_16x16x32_bf16 v[20:23], v[168:171], v[208:211], v[20:23]
	v_mfma_f32_16x16x32_bf16 v[20:23], v[172:175], v[212:215], v[20:23]
	v_mfma_f32_16x16x32_bf16 v[12:15], v[176:179], v[208:211], v[12:15]
	v_mfma_f32_16x16x32_bf16 v[12:15], v[180:183], v[212:215], v[12:15]
	s_setprio 2
	s_barrier
	v_mfma_f32_16x16x32_bf16 v[8:11], v[168:171], v[216:219], v[8:11]
	v_mfma_f32_16x16x32_bf16 v[8:11], v[172:175], v[220:223], v[8:11]
	v_mfma_f32_16x16x32_bf16 v[4:7], v[176:179], v[216:219], v[4:7]
	v_mfma_f32_16x16x32_bf16 v[4:7], v[180:183], v[220:223], v[4:7]
	s_setprio 0
	s_add_i32 s27, 0, 0x18000
	v_add_u32_e32 v158, s27, v145
	s_add_i32 s65, 0, 0x1c000
	ds_read_b128 v[140:143], v158
	ds_read_b128 v[148:151], v158 offset:1024
	ds_read_b128 v[152:155], v158 offset:2048
	ds_read_b128 v[164:167], v158 offset:3072
	v_add_u32_e32 v158, s65, v145
	ds_read_b128 v[168:171], v158
	ds_read_b128 v[172:175], v158 offset:1024
	ds_read_b128 v[176:179], v158 offset:2048
	ds_read_b128 v[180:183], v158 offset:3072
	s_add_u32 s30, s42, 0x80000
	s_addc_u32 s31, s43, 0
	s_mov_b32 m0, s60
	v_lshl_add_u64 v[228:229], s[30:31], 0, v[134:135]
	ds_read_b128 v[184:187], v147 offset:32768
	ds_read_b128 v[188:191], v147 offset:33792
	ds_read_b128 v[192:195], v147 offset:34816
	ds_read_b128 v[204:207], v147 offset:35840
	ds_read_b128 v[208:211], v147 offset:36864
	ds_read_b128 v[212:215], v147 offset:37888
	ds_read_b128 v[216:219], v147 offset:38912
	ds_read_b128 v[220:223], v147 offset:39936
	global_load_lds_dwordx4 v[228:229], off
	v_lshl_add_u64 v[228:229], s[30:31], 0, v[132:133]
	s_mov_b32 m0, s61
	s_nop 0
	global_load_lds_dwordx4 v[228:229], off
	s_waitcnt vmcnt(8)
	s_waitcnt lgkmcnt(0)
	s_barrier
	s_setprio 1
	s_waitcnt lgkmcnt(0)
	v_mfma_f32_16x16x32_bf16 v[128:131], v[140:143], v[184:187], v[128:131]
	v_mfma_f32_16x16x32_bf16 v[128:131], v[148:151], v[188:191], v[128:131]
	v_mfma_f32_16x16x32_bf16 v[124:127], v[152:155], v[184:187], v[124:127]
	v_mfma_f32_16x16x32_bf16 v[124:127], v[164:167], v[188:191], v[124:127]
	v_mfma_f32_16x16x32_bf16 v[120:123], v[140:143], v[192:195], v[120:123]
	v_mfma_f32_16x16x32_bf16 v[120:123], v[148:151], v[204:207], v[120:123]
	v_mfma_f32_16x16x32_bf16 v[112:115], v[152:155], v[192:195], v[112:115]
	v_mfma_f32_16x16x32_bf16 v[112:115], v[164:167], v[204:207], v[112:115]
	v_mfma_f32_16x16x32_bf16 v[104:107], v[140:143], v[208:211], v[104:107]
	v_mfma_f32_16x16x32_bf16 v[104:107], v[148:151], v[212:215], v[104:107]
	v_mfma_f32_16x16x32_bf16 v[96:99], v[152:155], v[208:211], v[96:99]
	v_mfma_f32_16x16x32_bf16 v[96:99], v[164:167], v[212:215], v[96:99]
	v_mfma_f32_16x16x32_bf16 v[88:91], v[140:143], v[216:219], v[88:91]
	v_mfma_f32_16x16x32_bf16 v[88:91], v[148:151], v[220:223], v[88:91]
	v_mfma_f32_16x16x32_bf16 v[80:83], v[152:155], v[216:219], v[80:83]
	v_mfma_f32_16x16x32_bf16 v[80:83], v[164:167], v[220:223], v[80:83]
	s_setprio 0
	s_setprio 1
	v_mfma_f32_16x16x32_bf16 v[116:119], v[168:171], v[184:187], v[116:119]
	v_mfma_f32_16x16x32_bf16 v[116:119], v[172:175], v[188:191], v[116:119]
	v_mfma_f32_16x16x32_bf16 v[108:111], v[176:179], v[184:187], v[108:111]
	v_mfma_f32_16x16x32_bf16 v[108:111], v[180:183], v[188:191], v[108:111]
	v_mfma_f32_16x16x32_bf16 v[100:103], v[168:171], v[192:195], v[100:103]
	v_mfma_f32_16x16x32_bf16 v[100:103], v[172:175], v[204:207], v[100:103]
	v_mfma_f32_16x16x32_bf16 v[92:95], v[176:179], v[192:195], v[92:95]
	v_mfma_f32_16x16x32_bf16 v[92:95], v[180:183], v[204:207], v[92:95]
	v_mfma_f32_16x16x32_bf16 v[84:87], v[168:171], v[208:211], v[84:87]
	v_mfma_f32_16x16x32_bf16 v[84:87], v[172:175], v[212:215], v[84:87]
	v_mfma_f32_16x16x32_bf16 v[76:79], v[176:179], v[208:211], v[76:79]
	v_mfma_f32_16x16x32_bf16 v[76:79], v[180:183], v[212:215], v[76:79]
	s_setprio 2
	s_barrier
; #define PG8_STAGE(bufoff, gbase, voff) do { _Pragma("unroll") for (int _i = 0; _i < 2; ++_i) \
;         __builtin_amdgcn_global_load_lds((const unsigned*)((const char*)(gbase) + (voff)[_i]), (LAS unsigned*)(lds + (bufoff) + ldsw + _i * 8192), 16, 0, 0); } while (0)
; #define PG8_LDA(dst, b, h) do { _Pragma("unroll") for (int m = 0; m < 4; ++m) _Pragma("unroll") for (int k = 0; k < 2; ++k) dst[m][k] = *(const LAS bf16x8*)(lds + PG8_SA(b, h) + aoff + m * 2048 + k * 1024); } while (0)
; #define PG8_MMA(ai, bj, At, Bt) do { __builtin_amdgcn_s_setprio(1); _Pragma("unroll") for (int m = 0; m < 4; ++m) _Pragma("unroll") for (int n = 0; n < 2; ++n) _Pragma("unroll") for (int k = 0; k < 2; ++k) \
;         acc[ai][bj][m][n] = __builtin_amdgcn_mfma_f32_16x16x32_bf16(Bt[n][k], At[m][k], acc[ai][bj][m][n], 0, 0, 0); __builtin_amdgcn_s_setprio(0); } while (0)
; #define PG8_WAIT_V(n) asm volatile("s_waitcnt vmcnt(" #n ")" ::: "memory")
; #define PG8_WAIT_L(n) asm volatile("s_waitcnt lgkmcnt(" #n ")" ::: "memory")
; #define PG8_BAR __builtin_amdgcn_s_barrier()
; #define PG8_SCHED __builtin_amdgcn_sched_barrier(0)
; template <class Epi, class Sched, bool ALIGN_EPI = true>
; __device__ __forceinline__ void gemm_phase(LAS unsigned char* lds, const Gemm g, const Sched& S, const Epi& E) {
;     ...
;             PG8_WAIT_V(8); PG8_WAIT_L(0); PG8_BAR; PG8_MMA(0, 0, At, B0); PG8_MMA(0, 1, At, B1); PG8_BAR; PG8_SCHED;
;             PG8_LDA(At, 1, 1); PG8_STAGE(PG8_SB(1, 0), b3, voffB); PG8_STAGE(PG8_SB(1, 1), b3 + hB, voffB); PG8_STAGE(PG8_SA(1, 0), a3, voffA);
;             PG8_WAIT_V(8); PG8_WAIT_L(0); PG8_BAR; PG8_MMA(1, 0, At, B0); PG8_MMA(1, 1, At, B1); PG8_BAR; PG8_SCHED;
;         }
;         if constexpr (ALIGN_EPI) { if (wr == 0) PG8_BAR; }
	v_mfma_f32_16x16x32_bf16 v[72:75], v[168:171], v[216:219], v[72:75]
	v_mfma_f32_16x16x32_bf16 v[72:75], v[172:175], v[220:223], v[72:75]
	v_mfma_f32_16x16x32_bf16 v[68:71], v[176:179], v[216:219], v[68:71]
	v_mfma_f32_16x16x32_bf16 v[68:71], v[180:183], v[220:223], v[68:71]
	s_setprio 0
	s_add_i32 s27, s27, s53
	v_lshl_add_u64 v[156:157], v[156:157], 0, s[86:87]
	s_mov_b32 m0, s27
	ds_read_b128 v[184:187], v147 offset:49152
	ds_read_b128 v[188:191], v147 offset:50176
	ds_read_b128 v[192:195], v147 offset:51200
	ds_read_b128 v[204:207], v147 offset:52224
	ds_read_b128 v[208:211], v147 offset:53248
	ds_read_b128 v[212:215], v147 offset:54272
	ds_read_b128 v[216:219], v147 offset:55296
	ds_read_b128 v[220:223], v147 offset:56320
	global_load_lds_dwordx4 v[156:157], off
	s_add_i32 m0, s27, 0x2000
	s_add_u32 s30, s40, 0x80080
	v_lshl_add_u64 v[156:157], v[196:197], 0, s[86:87]
	s_addc_u32 s31, s41, 0
	s_add_i32 s27, s65, s53
	global_load_lds_dwordx4 v[156:157], off
	v_lshl_add_u64 v[156:157], s[30:31], 0, v[2:3]
	s_mov_b32 m0, s27
	s_nop 0
	global_load_lds_dwordx4 v[156:157], off
	v_lshl_add_u64 v[156:157], s[30:31], 0, v[0:1]
	s_add_i32 m0, s27, 0x2000
	s_nop 0
	global_load_lds_dwordx4 v[156:157], off
	v_lshl_add_u64 v[156:157], v[224:225], 0, s[86:87]
	s_mov_b32 m0, s62
	s_nop 0
	global_load_lds_dwordx4 v[156:157], off
	v_lshl_add_u64 v[156:157], v[226:227], 0, s[86:87]
	s_mov_b32 m0, s63
	s_nop 0
	global_load_lds_dwordx4 v[156:157], off
	s_waitcnt vmcnt(8)
	s_waitcnt lgkmcnt(0)
	s_barrier
	s_setprio 1
	s_waitcnt lgkmcnt(0)
	v_mfma_f32_16x16x32_bf16 v[64:67], v[140:143], v[184:187], v[64:67]
	v_mfma_f32_16x16x32_bf16 v[64:67], v[148:151], v[188:191], v[64:67]
	v_mfma_f32_16x16x32_bf16 v[60:63], v[152:155], v[184:187], v[60:63]
	v_mfma_f32_16x16x32_bf16 v[60:63], v[164:167], v[188:191], v[60:63]
	v_mfma_f32_16x16x32_bf16 v[56:59], v[140:143], v[192:195], v[56:59]
	v_mfma_f32_16x16x32_bf16 v[56:59], v[148:151], v[204:207], v[56:59]
	v_mfma_f32_16x16x32_bf16 v[48:51], v[152:155], v[192:195], v[48:51]
	v_mfma_f32_16x16x32_bf16 v[48:51], v[164:167], v[204:207], v[48:51]
	v_mfma_f32_16x16x32_bf16 v[40:43], v[140:143], v[208:211], v[40:43]
	v_mfma_f32_16x16x32_bf16 v[40:43], v[148:151], v[212:215], v[40:43]
	v_mfma_f32_16x16x32_bf16 v[32:35], v[152:155], v[208:211], v[32:35]
	v_mfma_f32_16x16x32_bf16 v[32:35], v[164:167], v[212:215], v[32:35]
	v_mfma_f32_16x16x32_bf16 v[24:27], v[140:143], v[216:219], v[24:27]
	v_mfma_f32_16x16x32_bf16 v[24:27], v[148:151], v[220:223], v[24:27]
	v_mfma_f32_16x16x32_bf16 v[16:19], v[152:155], v[216:219], v[16:19]
	v_mfma_f32_16x16x32_bf16 v[16:19], v[164:167], v[220:223], v[16:19]
	s_setprio 0
	s_setprio 1
	v_mfma_f32_16x16x32_bf16 v[52:55], v[168:171], v[184:187], v[52:55]
	v_mfma_f32_16x16x32_bf16 v[52:55], v[172:175], v[188:191], v[52:55]
	v_mfma_f32_16x16x32_bf16 v[44:47], v[176:179], v[184:187], v[44:47]
	v_mfma_f32_16x16x32_bf16 v[44:47], v[180:183], v[188:191], v[44:47]
	v_mfma_f32_16x16x32_bf16 v[36:39], v[168:171], v[192:195], v[36:39]
	v_mfma_f32_16x16x32_bf16 v[36:39], v[172:175], v[204:207], v[36:39]
	v_mfma_f32_16x16x32_bf16 v[28:31], v[176:179], v[192:195], v[28:31]
	v_mfma_f32_16x16x32_bf16 v[28:31], v[180:183], v[204:207], v[28:31]
	v_mfma_f32_16x16x32_bf16 v[20:23], v[168:171], v[208:211], v[20:23]
	v_mfma_f32_16x16x32_bf16 v[20:23], v[172:175], v[212:215], v[20:23]
	v_mfma_f32_16x16x32_bf16 v[12:15], v[176:179], v[208:211], v[12:15]
	v_mfma_f32_16x16x32_bf16 v[12:15], v[180:183], v[212:215], v[12:15]
	s_setprio 2
	s_barrier
	v_mfma_f32_16x16x32_bf16 v[8:11], v[168:171], v[216:219], v[8:11]
	v_mfma_f32_16x16x32_bf16 v[8:11], v[172:175], v[220:223], v[8:11]
	v_mfma_f32_16x16x32_bf16 v[4:7], v[176:179], v[216:219], v[4:7]
	v_mfma_f32_16x16x32_bf16 v[4:7], v[180:183], v[220:223], v[4:7]
	s_setprio 0
	s_add_i32 s26, s26, 2
	s_add_u32 s38, s38, 0x100
	s_addc_u32 s39, s39, 0
	s_add_u32 s24, s24, 0x100
	s_addc_u32 s25, s25, 0
	s_cmp_gt_u32 s26, 29
	s_cbranch_scc0 .LBB0_218
	s_and_b64 vcc, exec, s[6:7]
	s_cbranch_vccz .LBB0_221
	s_barrier

; #define PG8_STAGE(bufoff, gbase, voff) do { _Pragma("unroll") for (int _i = 0; _i < 2; ++_i) \
;         __builtin_amdgcn_global_load_lds((const unsigned*)((const char*)(gbase) + (voff)[_i]), (LAS unsigned*)(lds + (bufoff) + ldsw + _i * 8192), 16, 0, 0); } while (0)
; #define PG8_LDA(dst, b, h) do { _Pragma("unroll") for (int m = 0; m < 4; ++m) _Pragma("unroll") for (int k = 0; k < 2; ++k) dst[m][k] = *(const LAS bf16x8*)(lds + PG8_SA(b, h) + aoff + m * 2048 + k * 1024); } while (0)
; #define PG8_LDB(dst, b, h) do { _Pragma("unroll") for (int n = 0; n < 2; ++n) _Pragma("unroll") for (int k = 0; k < 2; ++k) dst[n][k] = *(const LAS bf16x8*)(lds + PG8_SB(b, h) + boff + n * 2048 + k * 1024); } while (0)
; #define PG8_MMA(ai, bj, At, Bt) do { __builtin_amdgcn_s_setprio(1); _Pragma("unroll") for (int m = 0; m < 4; ++m) _Pragma("unroll") for (int n = 0; n < 2; ++n) _Pragma("unroll") for (int k = 0; k < 2; ++k) \
;         acc[ai][bj][m][n] = __builtin_amdgcn_mfma_f32_16x16x32_bf16(Bt[n][k], At[m][k], acc[ai][bj][m][n], 0, 0, 0); __builtin_amdgcn_s_setprio(0); } while (0)
; #define PG8_WAIT_V(n) asm volatile("s_waitcnt vmcnt(" #n ")" ::: "memory")
; #define PG8_WAIT_L(n) asm volatile("s_waitcnt lgkmcnt(" #n ")" ::: "memory")
; #define PG8_BAR __builtin_amdgcn_s_barrier()
; #define PG8_SCHED __builtin_amdgcn_sched_barrier(0)
; template <class Epi, class Sched, bool ALIGN_EPI = true>
; __device__ __forceinline__ void gemm_phase(LAS unsigned char* lds, const Gemm g, const Sched& S, const Epi& E) {
;     ...
;             const bool last = (t == nt - 2);
;             const char* a1 = cA + (size_t)(t + 1) * kstep;
;             const char* a2 = last ? nA : cA + (size_t)(t + 2) * kstep; const char* b2 = last ? nB : cB + (size_t)(t + 2) * kstep;
;             const char* a3 = a2 + kstep; const char* b3 = b2 + kstep;
;             PG8_LDB(B0, 0, 0); PG8_LDB(B1, 0, 1); PG8_SCHED; PG8_LDA(At, 0, 0); PG8_STAGE(PG8_SA(1, 1), a1 + hA, voffA);
;             PG8_WAIT_V(8); PG8_WAIT_L(0); PG8_BAR; PG8_MMA(0, 0, At, B0); PG8_MMA(0, 1, At, B1); PG8_BAR; PG8_SCHED;
;             PG8_LDA(At, 0, 1); PG8_STAGE(PG8_SB(0, 0), b2, voffB); PG8_STAGE(PG8_SB(0, 1), b2 + hB, voffB); PG8_STAGE(PG8_SA(0, 0), a2, voffA);
;             PG8_WAIT_V(8); PG8_WAIT_L(0); PG8_BAR; PG8_MMA(1, 0, At, B0); PG8_MMA(1, 1, At, B1); PG8_BAR; PG8_SCHED;
.LBB0_667:
	s_add_u32 vcc_lo, s10, 0x100
	s_addc_u32 vcc_hi, s11, 0
	s_add_u32 s25, s18, s10
	s_addc_u32 s26, s19, s11
	s_add_i32 s27, 0, 0x10000
	s_cmp_eq_u32 s24, 28
	s_cselect_b32 s65, s16, s26
	s_cselect_b32 s26, 0, vcc_lo
	s_cselect_b32 s64, s17, s25
	s_cselect_b32 s25, 0, vcc_hi
	s_add_u32 s62, s14, s26
	v_add_u32_e32 v160, s27, v186
	s_addc_u32 s63, s15, s25
	s_add_i32 s25, 0, 0x14000
	ds_read_b128 v[136:139], v160
	ds_read_b128 v[140:143], v160 offset:1024
	ds_read_b128 v[144:147], v160 offset:2048
	ds_read_b128 v[170:173], v160 offset:3072
	v_add_u32_e32 v160, s25, v186
	ds_read_b128 v[174:177], v160
	ds_read_b128 v[178:181], v160 offset:1024
	ds_read_b128 v[182:185], v160 offset:2048
	ds_read_b128 v[208:211], v160 offset:3072
	v_lshl_add_u64 v[244:245], v[132:133], 0, s[10:11]
	s_add_i32 m0, s53, 0xc000
	ds_read_b128 v[212:215], v197
	ds_read_b128 v[216:219], v197 offset:1024
	ds_read_b128 v[220:223], v197 offset:2048
	ds_read_b128 v[224:227], v197 offset:3072
	ds_read_b128 v[228:231], v197 offset:4096
	ds_read_b128 v[232:235], v197 offset:5120
	ds_read_b128 v[236:239], v197 offset:6144
	ds_read_b128 v[240:243], v197 offset:7168
	global_load_lds_dwordx4 v[244:245], off
	v_lshl_add_u64 v[244:245], v[134:135], 0, s[10:11]
	s_add_i32 m0, s53, 0xe000
	s_nop 0
	global_load_lds_dwordx4 v[244:245], off
	s_waitcnt vmcnt(8)
	s_waitcnt lgkmcnt(0)
	s_barrier
	s_setprio 1
	s_waitcnt lgkmcnt(0)
	v_mfma_f32_16x16x32_bf16 v[36:39], v[136:139], v[212:215], v[36:39]
	v_mfma_f32_16x16x32_bf16 v[36:39], v[140:143], v[216:219], v[36:39]
	v_mfma_f32_16x16x32_bf16 v[40:43], v[144:147], v[212:215], v[40:43]
	v_mfma_f32_16x16x32_bf16 v[40:43], v[170:173], v[216:219], v[40:43]
	v_mfma_f32_16x16x32_bf16 v[68:71], v[136:139], v[220:223], v[68:71]
	v_mfma_f32_16x16x32_bf16 v[68:71], v[140:143], v[224:227], v[68:71]
	v_mfma_f32_16x16x32_bf16 v[72:75], v[144:147], v[220:223], v[72:75]
	v_mfma_f32_16x16x32_bf16 v[72:75], v[170:173], v[224:227], v[72:75]
	v_mfma_f32_16x16x32_bf16 v[100:103], v[136:139], v[228:231], v[100:103]
	v_mfma_f32_16x16x32_bf16 v[100:103], v[140:143], v[232:235], v[100:103]
	v_mfma_f32_16x16x32_bf16 v[104:107], v[144:147], v[228:231], v[104:107]
	v_mfma_f32_16x16x32_bf16 v[104:107], v[170:173], v[232:235], v[104:107]
	v_mfma_f32_16x16x32_bf16 v[128:131], v[136:139], v[236:239], v[128:131]
	v_mfma_f32_16x16x32_bf16 v[128:131], v[140:143], v[240:243], v[128:131]
	v_mfma_f32_16x16x32_bf16 v[124:127], v[144:147], v[236:239], v[124:127]
	v_mfma_f32_16x16x32_bf16 v[124:127], v[170:173], v[240:243], v[124:127]
	s_setprio 0
	s_setprio 1
	v_mfma_f32_16x16x32_bf16 v[8:11], v[174:177], v[212:215], v[8:11]
	v_mfma_f32_16x16x32_bf16 v[8:11], v[178:181], v[216:219], v[8:11]
	v_mfma_f32_16x16x32_bf16 v[4:7], v[182:185], v[212:215], v[4:7]
	v_mfma_f32_16x16x32_bf16 v[4:7], v[208:211], v[216:219], v[4:7]
	v_mfma_f32_16x16x32_bf16 v[32:35], v[174:177], v[220:223], v[32:35]
	v_mfma_f32_16x16x32_bf16 v[32:35], v[178:181], v[224:227], v[32:35]
	v_mfma_f32_16x16x32_bf16 v[28:31], v[182:185], v[220:223], v[28:31]
	v_mfma_f32_16x16x32_bf16 v[28:31], v[208:211], v[224:227], v[28:31]
	v_mfma_f32_16x16x32_bf16 v[56:59], v[174:177], v[228:231], v[56:59]
	v_mfma_f32_16x16x32_bf16 v[56:59], v[178:181], v[232:235], v[56:59]
	v_mfma_f32_16x16x32_bf16 v[52:55], v[182:185], v[228:231], v[52:55]
	v_mfma_f32_16x16x32_bf16 v[52:55], v[208:211], v[232:235], v[52:55]
	s_setprio 2
	s_barrier
	v_mfma_f32_16x16x32_bf16 v[80:83], v[174:177], v[236:239], v[80:83]
	v_mfma_f32_16x16x32_bf16 v[80:83], v[178:181], v[240:243], v[80:83]
	v_mfma_f32_16x16x32_bf16 v[76:79], v[182:185], v[236:239], v[76:79]
	v_mfma_f32_16x16x32_bf16 v[76:79], v[208:211], v[240:243], v[76:79]
	s_setprio 0
	s_add_i32 s10, s27, s67
	v_lshl_add_u64 v[244:245], s[62:63], 0, v[2:3]
	s_mov_b32 m0, s10
	ds_read_b128 v[212:215], v197 offset:16384
	ds_read_b128 v[216:219], v197 offset:17408
	ds_read_b128 v[220:223], v197 offset:18432
	ds_read_b128 v[224:227], v197 offset:19456
	ds_read_b128 v[228:231], v197 offset:20480
	ds_read_b128 v[232:235], v197 offset:21504
	ds_read_b128 v[236:239], v197 offset:22528
	ds_read_b128 v[240:243], v197 offset:23552
	global_load_lds_dwordx4 v[244:245], off
	s_add_i32 m0, s10, 0x2000
	s_add_u32 s10, s62, 0x80000
	v_lshl_add_u64 v[246:247], s[62:63], 0, v[150:151]
	s_addc_u32 s11, s63, 0
	s_add_i32 s25, s25, s67
	global_load_lds_dwordx4 v[246:247], off
	v_lshl_add_u64 v[248:249], s[10:11], 0, v[2:3]
	s_mov_b32 m0, s25
	v_lshl_add_u64 v[160:161], s[64:65], 0, v[148:149]
	global_load_lds_dwordx4 v[248:249], off
	v_lshl_add_u64 v[248:249], s[10:11], 0, v[150:151]
	s_add_i32 m0, s25, 0x2000
	s_nop 0
	global_load_lds_dwordx4 v[248:249], off
	v_lshl_add_u64 v[248:249], s[64:65], 0, v[0:1]
	s_mov_b32 m0, s53
	s_nop 0
	global_load_lds_dwordx4 v[248:249], off
	s_mov_b32 m0, s66
	s_nop 0
	global_load_lds_dwordx4 v[160:161], off
	s_waitcnt vmcnt(8)
	s_waitcnt lgkmcnt(0)
	s_barrier
; #define PG8_STAGE(bufoff, gbase, voff) do { _Pragma("unroll") for (int _i = 0; _i < 2; ++_i) \
;         __builtin_amdgcn_global_load_lds((const unsigned*)((const char*)(gbase) + (voff)[_i]), (LAS unsigned*)(lds + (bufoff) + ldsw + _i * 8192), 16, 0, 0); } while (0)
; #define PG8_LDA(dst, b, h) do { _Pragma("unroll") for (int m = 0; m < 4; ++m) _Pragma("unroll") for (int k = 0; k < 2; ++k) dst[m][k] = *(const LAS bf16x8*)(lds + PG8_SA(b, h) + aoff + m * 2048 + k * 1024); } while (0)
; #define PG8_LDB(dst, b, h) do { _Pragma("unroll") for (int n = 0; n < 2; ++n) _Pragma("unroll") for (int k = 0; k < 2; ++k) dst[n][k] = *(const LAS bf16x8*)(lds + PG8_SB(b, h) + boff + n * 2048 + k * 1024); } while (0)
; #define PG8_MMA(ai, bj, At, Bt) do { __builtin_amdgcn_s_setprio(1); _Pragma("unroll") for (int m = 0; m < 4; ++m) _Pragma("unroll") for (int n = 0; n < 2; ++n) _Pragma("unroll") for (int k = 0; k < 2; ++k) \
;         acc[ai][bj][m][n] = __builtin_amdgcn_mfma_f32_16x16x32_bf16(Bt[n][k], At[m][k], acc[ai][bj][m][n], 0, 0, 0); __builtin_amdgcn_s_setprio(0); } while (0)
; #define PG8_WAIT_V(n) asm volatile("s_waitcnt vmcnt(" #n ")" ::: "memory")
; #define PG8_WAIT_L(n) asm volatile("s_waitcnt lgkmcnt(" #n ")" ::: "memory")
; #define PG8_BAR __builtin_amdgcn_s_barrier()
; #define PG8_SCHED __builtin_amdgcn_sched_barrier(0)
; template <class Epi, class Sched, bool ALIGN_EPI = true>
; __device__ __forceinline__ void gemm_phase(LAS unsigned char* lds, const Gemm g, const Sched& S, const Epi& E) {
;     ...
;             PG8_WAIT_V(8); PG8_WAIT_L(0); PG8_BAR; PG8_MMA(1, 0, At, B0); PG8_MMA(1, 1, At, B1); PG8_BAR; PG8_SCHED;
;             PG8_LDB(B0, 1, 0); PG8_LDB(B1, 1, 1); PG8_SCHED; PG8_LDA(At, 1, 0); PG8_STAGE(PG8_SA(0, 1), a2 + hA, voffA);
;             PG8_WAIT_V(8); PG8_WAIT_L(0); PG8_BAR; PG8_MMA(0, 0, At, B0); PG8_MMA(0, 1, At, B1); PG8_BAR; PG8_SCHED;
	s_setprio 1
	s_waitcnt lgkmcnt(0)
	v_mfma_f32_16x16x32_bf16 v[120:123], v[136:139], v[212:215], v[120:123]
	v_mfma_f32_16x16x32_bf16 v[120:123], v[140:143], v[216:219], v[120:123]
	v_mfma_f32_16x16x32_bf16 v[116:119], v[144:147], v[212:215], v[116:119]
	v_mfma_f32_16x16x32_bf16 v[116:119], v[170:173], v[216:219], v[116:119]
	v_mfma_f32_16x16x32_bf16 v[96:99], v[136:139], v[220:223], v[96:99]
	v_mfma_f32_16x16x32_bf16 v[96:99], v[140:143], v[224:227], v[96:99]
	v_mfma_f32_16x16x32_bf16 v[92:95], v[144:147], v[220:223], v[92:95]
	v_mfma_f32_16x16x32_bf16 v[92:95], v[170:173], v[224:227], v[92:95]
	v_mfma_f32_16x16x32_bf16 v[64:67], v[136:139], v[228:231], v[64:67]
	v_mfma_f32_16x16x32_bf16 v[64:67], v[140:143], v[232:235], v[64:67]
	v_mfma_f32_16x16x32_bf16 v[60:63], v[144:147], v[228:231], v[60:63]
	v_mfma_f32_16x16x32_bf16 v[60:63], v[170:173], v[232:235], v[60:63]
	v_mfma_f32_16x16x32_bf16 v[24:27], v[136:139], v[236:239], v[24:27]
	v_mfma_f32_16x16x32_bf16 v[24:27], v[140:143], v[240:243], v[24:27]
	v_mfma_f32_16x16x32_bf16 v[20:23], v[144:147], v[236:239], v[20:23]
	v_mfma_f32_16x16x32_bf16 v[20:23], v[170:173], v[240:243], v[20:23]
	s_setprio 0
	s_setprio 1
	v_mfma_f32_16x16x32_bf16 v[112:115], v[174:177], v[212:215], v[112:115]
	v_mfma_f32_16x16x32_bf16 v[112:115], v[178:181], v[216:219], v[112:115]
	v_mfma_f32_16x16x32_bf16 v[108:111], v[182:185], v[212:215], v[108:111]
	v_mfma_f32_16x16x32_bf16 v[108:111], v[208:211], v[216:219], v[108:111]
	v_mfma_f32_16x16x32_bf16 v[88:91], v[174:177], v[220:223], v[88:91]
	v_mfma_f32_16x16x32_bf16 v[88:91], v[178:181], v[224:227], v[88:91]
	v_mfma_f32_16x16x32_bf16 v[84:87], v[182:185], v[220:223], v[84:87]
	v_mfma_f32_16x16x32_bf16 v[84:87], v[208:211], v[224:227], v[84:87]
	v_mfma_f32_16x16x32_bf16 v[48:51], v[174:177], v[228:231], v[48:51]
	v_mfma_f32_16x16x32_bf16 v[48:51], v[178:181], v[232:235], v[48:51]
	v_mfma_f32_16x16x32_bf16 v[44:47], v[182:185], v[228:231], v[44:47]
	v_mfma_f32_16x16x32_bf16 v[44:47], v[208:211], v[232:235], v[44:47]
	s_setprio 2
	s_barrier
	v_mfma_f32_16x16x32_bf16 v[16:19], v[174:177], v[236:239], v[16:19]
	v_mfma_f32_16x16x32_bf16 v[16:19], v[178:181], v[240:243], v[16:19]
	v_mfma_f32_16x16x32_bf16 v[12:15], v[182:185], v[236:239], v[12:15]
	v_mfma_f32_16x16x32_bf16 v[12:15], v[208:211], v[240:243], v[12:15]
	s_setprio 0
	s_add_i32 s25, 0, 0x18000
	v_add_u32_e32 v162, s25, v186
	s_add_i32 s26, 0, 0x1c000
	ds_read_b128 v[136:139], v162
	ds_read_b128 v[140:143], v162 offset:1024
	ds_read_b128 v[144:147], v162 offset:2048
	ds_read_b128 v[170:173], v162 offset:3072
	v_add_u32_e32 v162, s26, v186
	ds_read_b128 v[174:177], v162
	ds_read_b128 v[178:181], v162 offset:1024
	ds_read_b128 v[182:185], v162 offset:2048
	ds_read_b128 v[208:211], v162 offset:3072
	s_add_u32 s10, s64, 0x80000
	s_addc_u32 s11, s65, 0
	s_mov_b32 m0, s75
	v_lshl_add_u64 v[162:163], s[10:11], 0, v[0:1]
	ds_read_b128 v[212:215], v197 offset:32768
	ds_read_b128 v[216:219], v197 offset:33792
	ds_read_b128 v[220:223], v197 offset:34816
	ds_read_b128 v[224:227], v197 offset:35840
	ds_read_b128 v[228:231], v197 offset:36864
	ds_read_b128 v[232:235], v197 offset:37888
	ds_read_b128 v[236:239], v197 offset:38912
	ds_read_b128 v[240:243], v197 offset:39936
	global_load_lds_dwordx4 v[162:163], off
	v_lshl_add_u64 v[162:163], s[10:11], 0, v[148:149]
	s_mov_b32 m0, s76
	s_nop 0
	global_load_lds_dwordx4 v[162:163], off
	s_waitcnt vmcnt(8)
	s_waitcnt lgkmcnt(0)
	s_barrier
	s_setprio 1
	s_waitcnt lgkmcnt(0)
	v_mfma_f32_16x16x32_bf16 v[36:39], v[136:139], v[212:215], v[36:39]
	v_mfma_f32_16x16x32_bf16 v[36:39], v[140:143], v[216:219], v[36:39]
	v_mfma_f32_16x16x32_bf16 v[40:43], v[144:147], v[212:215], v[40:43]
	v_mfma_f32_16x16x32_bf16 v[40:43], v[170:173], v[216:219], v[40:43]
	v_mfma_f32_16x16x32_bf16 v[68:71], v[136:139], v[220:223], v[68:71]
	v_mfma_f32_16x16x32_bf16 v[68:71], v[140:143], v[224:227], v[68:71]
	v_mfma_f32_16x16x32_bf16 v[72:75], v[144:147], v[220:223], v[72:75]
	v_mfma_f32_16x16x32_bf16 v[72:75], v[170:173], v[224:227], v[72:75]
	v_mfma_f32_16x16x32_bf16 v[100:103], v[136:139], v[228:231], v[100:103]
	v_mfma_f32_16x16x32_bf16 v[100:103], v[140:143], v[232:235], v[100:103]
	v_mfma_f32_16x16x32_bf16 v[104:107], v[144:147], v[228:231], v[104:107]
	v_mfma_f32_16x16x32_bf16 v[104:107], v[170:173], v[232:235], v[104:107]
	v_mfma_f32_16x16x32_bf16 v[128:131], v[136:139], v[236:239], v[128:131]
	v_mfma_f32_16x16x32_bf16 v[128:131], v[140:143], v[240:243], v[128:131]
	v_mfma_f32_16x16x32_bf16 v[124:127], v[144:147], v[236:239], v[124:127]
	v_mfma_f32_16x16x32_bf16 v[124:127], v[170:173], v[240:243], v[124:127]
	s_setprio 0
	s_setprio 1
	v_mfma_f32_16x16x32_bf16 v[8:11], v[174:177], v[212:215], v[8:11]
	v_mfma_f32_16x16x32_bf16 v[8:11], v[178:181], v[216:219], v[8:11]
	v_mfma_f32_16x16x32_bf16 v[4:7], v[182:185], v[212:215], v[4:7]
	v_mfma_f32_16x16x32_bf16 v[4:7], v[208:211], v[216:219], v[4:7]
	v_mfma_f32_16x16x32_bf16 v[32:35], v[174:177], v[220:223], v[32:35]
	v_mfma_f32_16x16x32_bf16 v[32:35], v[178:181], v[224:227], v[32:35]
	v_mfma_f32_16x16x32_bf16 v[28:31], v[182:185], v[220:223], v[28:31]
	v_mfma_f32_16x16x32_bf16 v[28:31], v[208:211], v[224:227], v[28:31]
	v_mfma_f32_16x16x32_bf16 v[56:59], v[174:177], v[228:231], v[56:59]
	v_mfma_f32_16x16x32_bf16 v[56:59], v[178:181], v[232:235], v[56:59]
	v_mfma_f32_16x16x32_bf16 v[52:55], v[182:185], v[228:231], v[52:55]
	v_mfma_f32_16x16x32_bf16 v[52:55], v[208:211], v[232:235], v[52:55]
	s_setprio 2
	s_barrier
; #define PG8_STAGE(bufoff, gbase, voff) do { _Pragma("unroll") for (int _i = 0; _i < 2; ++_i) \
;         __builtin_amdgcn_global_load_lds((const unsigned*)((const char*)(gbase) + (voff)[_i]), (LAS unsigned*)(lds + (bufoff) + ldsw + _i * 8192), 16, 0, 0); } while (0)
; #define PG8_LDA(dst, b, h) do { _Pragma("unroll") for (int m = 0; m < 4; ++m) _Pragma("unroll") for (int k = 0; k < 2; ++k) dst[m][k] = *(const LAS bf16x8*)(lds + PG8_SA(b, h) + aoff + m * 2048 + k * 1024); } while (0)
; #define PG8_MMA(ai, bj, At, Bt) do { __builtin_amdgcn_s_setprio(1); _Pragma("unroll") for (int m = 0; m < 4; ++m) _Pragma("unroll") for (int n = 0; n < 2; ++n) _Pragma("unroll") for (int k = 0; k < 2; ++k) \
;         acc[ai][bj][m][n] = __builtin_amdgcn_mfma_f32_16x16x32_bf16(Bt[n][k], At[m][k], acc[ai][bj][m][n], 0, 0, 0); __builtin_amdgcn_s_setprio(0); } while (0)
; #define PG8_WAIT_V(n) asm volatile("s_waitcnt vmcnt(" #n ")" ::: "memory")
; #define PG8_WAIT_L(n) asm volatile("s_waitcnt lgkmcnt(" #n ")" ::: "memory")
; #define PG8_BAR __builtin_amdgcn_s_barrier()
; #define PG8_SCHED __builtin_amdgcn_sched_barrier(0)
; template <class Epi, class Sched, bool ALIGN_EPI = true>
; __device__ __forceinline__ void gemm_phase(LAS unsigned char* lds, const Gemm g, const Sched& S, const Epi& E) {
;     ...
;             PG8_WAIT_V(8); PG8_WAIT_L(0); PG8_BAR; PG8_MMA(0, 0, At, B0); PG8_MMA(0, 1, At, B1); PG8_BAR; PG8_SCHED;
;             PG8_LDA(At, 1, 1); PG8_STAGE(PG8_SB(1, 0), b3, voffB); PG8_STAGE(PG8_SB(1, 1), b3 + hB, voffB); PG8_STAGE(PG8_SA(1, 0), a3, voffA);
;             PG8_WAIT_V(8); PG8_WAIT_L(0); PG8_BAR; PG8_MMA(1, 0, At, B0); PG8_MMA(1, 1, At, B1); PG8_BAR; PG8_SCHED;
;         }
;         if constexpr (ALIGN_EPI) { if (wr == 0) PG8_BAR; }
	v_mfma_f32_16x16x32_bf16 v[80:83], v[174:177], v[236:239], v[80:83]
	v_mfma_f32_16x16x32_bf16 v[80:83], v[178:181], v[240:243], v[80:83]
	v_mfma_f32_16x16x32_bf16 v[76:79], v[182:185], v[236:239], v[76:79]
	v_mfma_f32_16x16x32_bf16 v[76:79], v[208:211], v[240:243], v[76:79]
	s_setprio 0
	s_add_i32 s10, s25, s67
	v_lshl_add_u64 v[162:163], v[244:245], 0, s[86:87]
	s_mov_b32 m0, s10
	ds_read_b128 v[212:215], v197 offset:49152
	ds_read_b128 v[216:219], v197 offset:50176
	ds_read_b128 v[220:223], v197 offset:51200
	ds_read_b128 v[224:227], v197 offset:52224
	ds_read_b128 v[228:231], v197 offset:53248
	ds_read_b128 v[232:235], v197 offset:54272
	ds_read_b128 v[236:239], v197 offset:55296
	ds_read_b128 v[240:243], v197 offset:56320
	global_load_lds_dwordx4 v[162:163], off
	s_add_i32 m0, s10, 0x2000
	s_add_u32 s10, s62, 0x80080
	v_lshl_add_u64 v[162:163], v[246:247], 0, s[86:87]
	s_addc_u32 s11, s63, 0
	s_add_i32 s25, s26, s67
	global_load_lds_dwordx4 v[162:163], off
	v_lshl_add_u64 v[162:163], s[10:11], 0, v[2:3]
	s_mov_b32 m0, s25
	v_lshl_add_u64 v[160:161], v[160:161], 0, s[86:87]
	global_load_lds_dwordx4 v[162:163], off
	v_lshl_add_u64 v[162:163], s[10:11], 0, v[150:151]
	s_add_i32 m0, s25, 0x2000
	s_nop 0
	global_load_lds_dwordx4 v[162:163], off
	v_lshl_add_u64 v[162:163], v[248:249], 0, s[86:87]
	s_mov_b32 m0, s79
	s_nop 0
	global_load_lds_dwordx4 v[162:163], off
	s_mov_b32 m0, s80
	s_nop 0
	global_load_lds_dwordx4 v[160:161], off
	s_waitcnt vmcnt(8)
	s_waitcnt lgkmcnt(0)
	s_barrier
	s_setprio 1
	s_waitcnt lgkmcnt(0)
	v_mfma_f32_16x16x32_bf16 v[120:123], v[136:139], v[212:215], v[120:123]
	v_mfma_f32_16x16x32_bf16 v[120:123], v[140:143], v[216:219], v[120:123]
	v_mfma_f32_16x16x32_bf16 v[116:119], v[144:147], v[212:215], v[116:119]
	v_mfma_f32_16x16x32_bf16 v[116:119], v[170:173], v[216:219], v[116:119]
	v_mfma_f32_16x16x32_bf16 v[96:99], v[136:139], v[220:223], v[96:99]
	v_mfma_f32_16x16x32_bf16 v[96:99], v[140:143], v[224:227], v[96:99]
	v_mfma_f32_16x16x32_bf16 v[92:95], v[144:147], v[220:223], v[92:95]
	v_mfma_f32_16x16x32_bf16 v[92:95], v[170:173], v[224:227], v[92:95]
	v_mfma_f32_16x16x32_bf16 v[64:67], v[136:139], v[228:231], v[64:67]
	v_mfma_f32_16x16x32_bf16 v[64:67], v[140:143], v[232:235], v[64:67]
	v_mfma_f32_16x16x32_bf16 v[60:63], v[144:147], v[228:231], v[60:63]
	v_mfma_f32_16x16x32_bf16 v[60:63], v[170:173], v[232:235], v[60:63]
	v_mfma_f32_16x16x32_bf16 v[24:27], v[136:139], v[236:239], v[24:27]
	v_mfma_f32_16x16x32_bf16 v[24:27], v[140:143], v[240:243], v[24:27]
	v_mfma_f32_16x16x32_bf16 v[20:23], v[144:147], v[236:239], v[20:23]
	v_mfma_f32_16x16x32_bf16 v[20:23], v[170:173], v[240:243], v[20:23]
	s_setprio 0
	s_setprio 1
	v_mfma_f32_16x16x32_bf16 v[112:115], v[174:177], v[212:215], v[112:115]
	v_mfma_f32_16x16x32_bf16 v[112:115], v[178:181], v[216:219], v[112:115]
	v_mfma_f32_16x16x32_bf16 v[108:111], v[182:185], v[212:215], v[108:111]
	v_mfma_f32_16x16x32_bf16 v[108:111], v[208:211], v[216:219], v[108:111]
	v_mfma_f32_16x16x32_bf16 v[88:91], v[174:177], v[220:223], v[88:91]
	v_mfma_f32_16x16x32_bf16 v[88:91], v[178:181], v[224:227], v[88:91]
	v_mfma_f32_16x16x32_bf16 v[84:87], v[182:185], v[220:223], v[84:87]
	v_mfma_f32_16x16x32_bf16 v[84:87], v[208:211], v[224:227], v[84:87]
	v_mfma_f32_16x16x32_bf16 v[48:51], v[174:177], v[228:231], v[48:51]
	v_mfma_f32_16x16x32_bf16 v[48:51], v[178:181], v[232:235], v[48:51]
	v_mfma_f32_16x16x32_bf16 v[44:47], v[182:185], v[228:231], v[44:47]
	v_mfma_f32_16x16x32_bf16 v[44:47], v[208:211], v[232:235], v[44:47]
	s_setprio 2
	s_barrier
	v_mfma_f32_16x16x32_bf16 v[16:19], v[174:177], v[236:239], v[16:19]
	v_mfma_f32_16x16x32_bf16 v[16:19], v[178:181], v[240:243], v[16:19]
	v_mfma_f32_16x16x32_bf16 v[12:15], v[182:185], v[236:239], v[12:15]
	v_mfma_f32_16x16x32_bf16 v[12:15], v[208:211], v[240:243], v[12:15]
	s_setprio 0
	s_add_i32 s24, s24, 2
	s_cmp_gt_u32 s24, 29
	s_mov_b64 s[10:11], vcc
	s_cbranch_scc0 .LBB0_667
	s_and_b64 vcc, exec, s[44:45]
	s_cbranch_vccz .LBB0_670
	s_barrier

; #define PG8_STAGE(bufoff, gbase, voff) do { _Pragma("unroll") for (int _i = 0; _i < 2; ++_i) \
;         __builtin_amdgcn_global_load_lds((const unsigned*)((const char*)(gbase) + (voff)[_i]), (LAS unsigned*)(lds + (bufoff) + ldsw + _i * 8192), 16, 0, 0); } while (0)
; #define PG8_LDA(dst, b, h) do { _Pragma("unroll") for (int m = 0; m < 4; ++m) _Pragma("unroll") for (int k = 0; k < 2; ++k) dst[m][k] = *(const LAS bf16x8*)(lds + PG8_SA(b, h) + aoff + m * 2048 + k * 1024); } while (0)
; #define PG8_LDB(dst, b, h) do { _Pragma("unroll") for (int n = 0; n < 2; ++n) _Pragma("unroll") for (int k = 0; k < 2; ++k) dst[n][k] = *(const LAS bf16x8*)(lds + PG8_SB(b, h) + boff + n * 2048 + k * 1024); } while (0)
; #define PG8_MMA(ai, bj, At, Bt) do { __builtin_amdgcn_s_setprio(1); _Pragma("unroll") for (int m = 0; m < 4; ++m) _Pragma("unroll") for (int n = 0; n < 2; ++n) _Pragma("unroll") for (int k = 0; k < 2; ++k) \
;         acc[ai][bj][m][n] = __builtin_amdgcn_mfma_f32_16x16x32_bf16(Bt[n][k], At[m][k], acc[ai][bj][m][n], 0, 0, 0); __builtin_amdgcn_s_setprio(0); } while (0)
; #define PG8_WAIT_V(n) asm volatile("s_waitcnt vmcnt(" #n ")" ::: "memory")
; #define PG8_WAIT_L(n) asm volatile("s_waitcnt lgkmcnt(" #n ")" ::: "memory")
; #define PG8_BAR __builtin_amdgcn_s_barrier()
; #define PG8_SCHED __builtin_amdgcn_sched_barrier(0)
; template <class Epi, class Sched, bool ALIGN_EPI = true>
; __device__ __forceinline__ void gemm_phase(LAS unsigned char* lds, const Gemm g, const Sched& S, const Epi& E) {
;     ...
;             const bool last = (t == nt - 2);
;             const char* a1 = cA + (size_t)(t + 1) * kstep;
;             const char* a2 = last ? nA : cA + (size_t)(t + 2) * kstep; const char* b2 = last ? nB : cB + (size_t)(t + 2) * kstep;
;             const char* a3 = a2 + kstep; const char* b3 = b2 + kstep;
;             PG8_LDB(B0, 0, 0); PG8_LDB(B1, 0, 1); PG8_SCHED; PG8_LDA(At, 0, 0); PG8_STAGE(PG8_SA(1, 1), a1 + hA, voffA);
;             PG8_WAIT_V(8); PG8_WAIT_L(0); PG8_BAR; PG8_MMA(0, 0, At, B0); PG8_MMA(0, 1, At, B1); PG8_BAR; PG8_SCHED;
;             PG8_LDA(At, 0, 1); PG8_STAGE(PG8_SB(0, 0), b2, voffB); PG8_STAGE(PG8_SB(0, 1), b2 + hB, voffB); PG8_STAGE(PG8_SA(0, 0), a2, voffA);
;             PG8_WAIT_V(8); PG8_WAIT_L(0); PG8_BAR; PG8_MMA(1, 0, At, B0); PG8_MMA(1, 1, At, B1); PG8_BAR; PG8_SCHED;
.LBB0_828:
	s_add_u32 s26, s6, 0xfff80080
	s_addc_u32 s27, s7, -1
	s_add_i32 s30, 0, 0x10000
	s_cmp_eq_u32 s25, 28
	s_cselect_b32 s59, s16, s27
	s_cselect_b32 s58, s17, s26
	v_add_u32_e32 v2, s30, v204
	s_cselect_b32 s45, s15, s24
	s_cselect_b32 s44, s18, s19
	s_add_i32 s31, 0, 0x14000
	ds_read_b128 v[132:135], v2
	ds_read_b128 v[136:139], v2 offset:1024
	ds_read_b128 v[140:143], v2 offset:2048
	ds_read_b128 v[144:147], v2 offset:3072
	v_add_u32_e32 v2, s31, v204
	ds_read_b128 v[148:151], v2
	ds_read_b128 v[152:155], v2 offset:1024
	ds_read_b128 v[174:177], v2 offset:2048
	ds_read_b128 v[178:181], v2 offset:3072
	v_lshl_add_u64 v[156:157], s[6:7], 0, v[170:171]
	s_add_i32 m0, s62, 0xc000
	ds_read_b128 v[182:185], v205
	ds_read_b128 v[186:189], v205 offset:1024
	ds_read_b128 v[190:193], v205 offset:2048
	ds_read_b128 v[194:197], v205 offset:3072
	ds_read_b128 v[206:209], v205 offset:4096
	ds_read_b128 v[210:213], v205 offset:5120
	ds_read_b128 v[214:217], v205 offset:6144
	ds_read_b128 v[218:221], v205 offset:7168
	global_load_lds_dwordx4 v[156:157], off
	v_lshl_add_u64 v[156:157], s[6:7], 0, v[172:173]
	s_add_i32 m0, s62, 0xe000
	s_nop 0
	global_load_lds_dwordx4 v[156:157], off
	s_waitcnt vmcnt(8)
	s_waitcnt lgkmcnt(0)
	s_barrier
	s_setprio 1
	s_waitcnt lgkmcnt(0)
	v_mfma_f32_16x16x32_bf16 v[116:119], v[132:135], v[182:185], v[116:119]
	v_mfma_f32_16x16x32_bf16 v[116:119], v[136:139], v[186:189], v[116:119]
	v_mfma_f32_16x16x32_bf16 v[100:103], v[140:143], v[182:185], v[100:103]
	v_mfma_f32_16x16x32_bf16 v[100:103], v[144:147], v[186:189], v[100:103]
	v_mfma_f32_16x16x32_bf16 v[108:111], v[132:135], v[190:193], v[108:111]
	v_mfma_f32_16x16x32_bf16 v[108:111], v[136:139], v[194:197], v[108:111]
	v_mfma_f32_16x16x32_bf16 v[96:99], v[140:143], v[190:193], v[96:99]
	v_mfma_f32_16x16x32_bf16 v[96:99], v[144:147], v[194:197], v[96:99]
	v_mfma_f32_16x16x32_bf16 v[88:91], v[132:135], v[206:209], v[88:91]
	v_mfma_f32_16x16x32_bf16 v[88:91], v[136:139], v[210:213], v[88:91]
	v_mfma_f32_16x16x32_bf16 v[84:87], v[140:143], v[206:209], v[84:87]
	v_mfma_f32_16x16x32_bf16 v[84:87], v[144:147], v[210:213], v[84:87]
	v_mfma_f32_16x16x32_bf16 v[72:75], v[132:135], v[214:217], v[72:75]
	v_mfma_f32_16x16x32_bf16 v[72:75], v[136:139], v[218:221], v[72:75]
	v_mfma_f32_16x16x32_bf16 v[80:83], v[140:143], v[214:217], v[80:83]
	v_mfma_f32_16x16x32_bf16 v[80:83], v[144:147], v[218:221], v[80:83]
	s_setprio 0
	s_setprio 1
	v_mfma_f32_16x16x32_bf16 v[128:131], v[148:151], v[182:185], v[128:131]
	v_mfma_f32_16x16x32_bf16 v[128:131], v[152:155], v[186:189], v[128:131]
	v_mfma_f32_16x16x32_bf16 v[44:47], v[174:177], v[182:185], v[44:47]
	v_mfma_f32_16x16x32_bf16 v[44:47], v[178:181], v[186:189], v[44:47]
	v_mfma_f32_16x16x32_bf16 v[124:127], v[148:151], v[190:193], v[124:127]
	v_mfma_f32_16x16x32_bf16 v[124:127], v[152:155], v[194:197], v[124:127]
	v_mfma_f32_16x16x32_bf16 v[36:39], v[174:177], v[190:193], v[36:39]
	v_mfma_f32_16x16x32_bf16 v[36:39], v[178:181], v[194:197], v[36:39]
	v_mfma_f32_16x16x32_bf16 v[120:123], v[148:151], v[206:209], v[120:123]
	v_mfma_f32_16x16x32_bf16 v[120:123], v[152:155], v[210:213], v[120:123]
	v_mfma_f32_16x16x32_bf16 v[32:35], v[174:177], v[206:209], v[32:35]
	v_mfma_f32_16x16x32_bf16 v[32:35], v[178:181], v[210:213], v[32:35]
	s_setprio 2
	s_barrier
	v_mfma_f32_16x16x32_bf16 v[112:115], v[148:151], v[214:217], v[112:115]
	v_mfma_f32_16x16x32_bf16 v[112:115], v[152:155], v[218:221], v[112:115]
	v_mfma_f32_16x16x32_bf16 v[28:31], v[174:177], v[214:217], v[28:31]
	v_mfma_f32_16x16x32_bf16 v[28:31], v[178:181], v[218:221], v[28:31]
	s_setprio 0
	s_add_i32 s26, s30, s61
	v_lshl_add_u64 v[156:157], s[44:45], 0, v[166:167]
	s_mov_b32 m0, s26
	ds_read_b128 v[182:185], v205 offset:16384
	ds_read_b128 v[186:189], v205 offset:17408
	ds_read_b128 v[190:193], v205 offset:18432
	ds_read_b128 v[194:197], v205 offset:19456
	ds_read_b128 v[206:209], v205 offset:20480
	ds_read_b128 v[210:213], v205 offset:21504
	ds_read_b128 v[214:217], v205 offset:22528
	ds_read_b128 v[218:221], v205 offset:23552
	global_load_lds_dwordx4 v[156:157], off
	s_add_i32 m0, s26, 0x2000
	s_add_u32 s26, s44, 0x80000
	v_lshl_add_u64 v[160:161], s[44:45], 0, v[0:1]
	s_addc_u32 s27, s45, 0
	s_add_i32 s30, s31, s61
	global_load_lds_dwordx4 v[160:161], off
	v_lshl_add_u64 v[162:163], s[26:27], 0, v[166:167]
	s_mov_b32 m0, s30
	v_lshl_add_u64 v[222:223], s[58:59], 0, v[164:165]
	global_load_lds_dwordx4 v[162:163], off
	v_lshl_add_u64 v[162:163], s[26:27], 0, v[0:1]
	s_add_i32 m0, s30, 0x2000
	s_nop 0
	global_load_lds_dwordx4 v[162:163], off
	v_lshl_add_u64 v[162:163], s[58:59], 0, v[168:169]
	s_mov_b32 m0, s62
	s_nop 0
	global_load_lds_dwordx4 v[162:163], off
	s_mov_b32 m0, s63
	s_nop 0
	global_load_lds_dwordx4 v[222:223], off
	s_waitcnt vmcnt(8)
	s_waitcnt lgkmcnt(0)
	s_barrier
; #define PG8_STAGE(bufoff, gbase, voff) do { _Pragma("unroll") for (int _i = 0; _i < 2; ++_i) \
;         __builtin_amdgcn_global_load_lds((const unsigned*)((const char*)(gbase) + (voff)[_i]), (LAS unsigned*)(lds + (bufoff) + ldsw + _i * 8192), 16, 0, 0); } while (0)
; #define PG8_LDA(dst, b, h) do { _Pragma("unroll") for (int m = 0; m < 4; ++m) _Pragma("unroll") for (int k = 0; k < 2; ++k) dst[m][k] = *(const LAS bf16x8*)(lds + PG8_SA(b, h) + aoff + m * 2048 + k * 1024); } while (0)
; #define PG8_LDB(dst, b, h) do { _Pragma("unroll") for (int n = 0; n < 2; ++n) _Pragma("unroll") for (int k = 0; k < 2; ++k) dst[n][k] = *(const LAS bf16x8*)(lds + PG8_SB(b, h) + boff + n * 2048 + k * 1024); } while (0)
; #define PG8_MMA(ai, bj, At, Bt) do { __builtin_amdgcn_s_setprio(1); _Pragma("unroll") for (int m = 0; m < 4; ++m) _Pragma("unroll") for (int n = 0; n < 2; ++n) _Pragma("unroll") for (int k = 0; k < 2; ++k) \
;         acc[ai][bj][m][n] = __builtin_amdgcn_mfma_f32_16x16x32_bf16(Bt[n][k], At[m][k], acc[ai][bj][m][n], 0, 0, 0); __builtin_amdgcn_s_setprio(0); } while (0)
; #define PG8_WAIT_V(n) asm volatile("s_waitcnt vmcnt(" #n ")" ::: "memory")
; #define PG8_WAIT_L(n) asm volatile("s_waitcnt lgkmcnt(" #n ")" ::: "memory")
; #define PG8_BAR __builtin_amdgcn_s_barrier()
; #define PG8_SCHED __builtin_amdgcn_sched_barrier(0)
; template <class Epi, class Sched, bool ALIGN_EPI = true>
; __device__ __forceinline__ void gemm_phase(LAS unsigned char* lds, const Gemm g, const Sched& S, const Epi& E) {
;     ...
;             PG8_WAIT_V(8); PG8_WAIT_L(0); PG8_BAR; PG8_MMA(1, 0, At, B0); PG8_MMA(1, 1, At, B1); PG8_BAR; PG8_SCHED;
;             PG8_LDB(B0, 1, 0); PG8_LDB(B1, 1, 1); PG8_SCHED; PG8_LDA(At, 1, 0); PG8_STAGE(PG8_SA(0, 1), a2 + hA, voffA);
;             PG8_WAIT_V(8); PG8_WAIT_L(0); PG8_BAR; PG8_MMA(0, 0, At, B0); PG8_MMA(0, 1, At, B1); PG8_BAR; PG8_SCHED;
	s_setprio 1
	s_waitcnt lgkmcnt(0)
	v_mfma_f32_16x16x32_bf16 v[60:63], v[132:135], v[182:185], v[60:63]
	v_mfma_f32_16x16x32_bf16 v[60:63], v[136:139], v[186:189], v[60:63]
	v_mfma_f32_16x16x32_bf16 v[68:71], v[140:143], v[182:185], v[68:71]
	v_mfma_f32_16x16x32_bf16 v[68:71], v[144:147], v[186:189], v[68:71]
	v_mfma_f32_16x16x32_bf16 v[40:43], v[132:135], v[190:193], v[40:43]
	v_mfma_f32_16x16x32_bf16 v[40:43], v[136:139], v[194:197], v[40:43]
	v_mfma_f32_16x16x32_bf16 v[64:67], v[140:143], v[190:193], v[64:67]
	v_mfma_f32_16x16x32_bf16 v[64:67], v[144:147], v[194:197], v[64:67]
	v_mfma_f32_16x16x32_bf16 v[24:27], v[132:135], v[206:209], v[24:27]
	v_mfma_f32_16x16x32_bf16 v[24:27], v[136:139], v[210:213], v[24:27]
	v_mfma_f32_16x16x32_bf16 v[56:59], v[140:143], v[206:209], v[56:59]
	v_mfma_f32_16x16x32_bf16 v[56:59], v[144:147], v[210:213], v[56:59]
	v_mfma_f32_16x16x32_bf16 v[12:15], v[132:135], v[214:217], v[12:15]
	v_mfma_f32_16x16x32_bf16 v[12:15], v[136:139], v[218:221], v[12:15]
	v_mfma_f32_16x16x32_bf16 v[48:51], v[140:143], v[214:217], v[48:51]
	v_mfma_f32_16x16x32_bf16 v[48:51], v[144:147], v[218:221], v[48:51]
	s_setprio 0
	s_setprio 1
	v_mfma_f32_16x16x32_bf16 v[104:107], v[148:151], v[182:185], v[104:107]
	v_mfma_f32_16x16x32_bf16 v[104:107], v[152:155], v[186:189], v[104:107]
	v_mfma_f32_16x16x32_bf16 v[20:23], v[174:177], v[182:185], v[20:23]
	v_mfma_f32_16x16x32_bf16 v[20:23], v[178:181], v[186:189], v[20:23]
	v_mfma_f32_16x16x32_bf16 v[92:95], v[148:151], v[190:193], v[92:95]
	v_mfma_f32_16x16x32_bf16 v[92:95], v[152:155], v[194:197], v[92:95]
	v_mfma_f32_16x16x32_bf16 v[16:19], v[174:177], v[190:193], v[16:19]
	v_mfma_f32_16x16x32_bf16 v[16:19], v[178:181], v[194:197], v[16:19]
	v_mfma_f32_16x16x32_bf16 v[76:79], v[148:151], v[206:209], v[76:79]
	v_mfma_f32_16x16x32_bf16 v[76:79], v[152:155], v[210:213], v[76:79]
	v_mfma_f32_16x16x32_bf16 v[8:11], v[174:177], v[206:209], v[8:11]
	v_mfma_f32_16x16x32_bf16 v[8:11], v[178:181], v[210:213], v[8:11]
	s_setprio 2
	s_barrier
	v_mfma_f32_16x16x32_bf16 v[52:55], v[148:151], v[214:217], v[52:55]
	v_mfma_f32_16x16x32_bf16 v[52:55], v[152:155], v[218:221], v[52:55]
	v_mfma_f32_16x16x32_bf16 v[4:7], v[174:177], v[214:217], v[4:7]
	v_mfma_f32_16x16x32_bf16 v[4:7], v[178:181], v[218:221], v[4:7]
	s_setprio 0
	s_add_i32 s30, 0, 0x18000
	v_add_u32_e32 v2, s30, v204
	s_add_i32 s31, 0, 0x1c000
	ds_read_b128 v[132:135], v2
	ds_read_b128 v[136:139], v2 offset:1024
	ds_read_b128 v[140:143], v2 offset:2048
	ds_read_b128 v[144:147], v2 offset:3072
	v_add_u32_e32 v2, s31, v204
	ds_read_b128 v[148:151], v2
	ds_read_b128 v[152:155], v2 offset:1024
	ds_read_b128 v[174:177], v2 offset:2048
	ds_read_b128 v[178:181], v2 offset:3072
	s_add_u32 s26, s58, 0x80000
	s_addc_u32 s27, s59, 0
	s_mov_b32 m0, s64
	v_lshl_add_u64 v[224:225], s[26:27], 0, v[168:169]
	ds_read_b128 v[182:185], v205 offset:32768
	ds_read_b128 v[186:189], v205 offset:33792
	ds_read_b128 v[190:193], v205 offset:34816
	ds_read_b128 v[194:197], v205 offset:35840
	ds_read_b128 v[206:209], v205 offset:36864
	ds_read_b128 v[210:213], v205 offset:37888
	ds_read_b128 v[214:217], v205 offset:38912
	ds_read_b128 v[218:221], v205 offset:39936
	global_load_lds_dwordx4 v[224:225], off
	v_lshl_add_u64 v[224:225], s[26:27], 0, v[164:165]
	s_mov_b32 m0, s65
	s_nop 0
	global_load_lds_dwordx4 v[224:225], off
	s_waitcnt vmcnt(8)
	s_waitcnt lgkmcnt(0)
	s_barrier
	s_setprio 1
	s_waitcnt lgkmcnt(0)
	v_mfma_f32_16x16x32_bf16 v[116:119], v[132:135], v[182:185], v[116:119]
	v_mfma_f32_16x16x32_bf16 v[116:119], v[136:139], v[186:189], v[116:119]
	v_mfma_f32_16x16x32_bf16 v[100:103], v[140:143], v[182:185], v[100:103]
	v_mfma_f32_16x16x32_bf16 v[100:103], v[144:147], v[186:189], v[100:103]
	v_mfma_f32_16x16x32_bf16 v[108:111], v[132:135], v[190:193], v[108:111]
	v_mfma_f32_16x16x32_bf16 v[108:111], v[136:139], v[194:197], v[108:111]
	v_mfma_f32_16x16x32_bf16 v[96:99], v[140:143], v[190:193], v[96:99]
	v_mfma_f32_16x16x32_bf16 v[96:99], v[144:147], v[194:197], v[96:99]
	v_mfma_f32_16x16x32_bf16 v[88:91], v[132:135], v[206:209], v[88:91]
	v_mfma_f32_16x16x32_bf16 v[88:91], v[136:139], v[210:213], v[88:91]
	v_mfma_f32_16x16x32_bf16 v[84:87], v[140:143], v[206:209], v[84:87]
	v_mfma_f32_16x16x32_bf16 v[84:87], v[144:147], v[210:213], v[84:87]
	v_mfma_f32_16x16x32_bf16 v[72:75], v[132:135], v[214:217], v[72:75]
	v_mfma_f32_16x16x32_bf16 v[72:75], v[136:139], v[218:221], v[72:75]
	v_mfma_f32_16x16x32_bf16 v[80:83], v[140:143], v[214:217], v[80:83]
	v_mfma_f32_16x16x32_bf16 v[80:83], v[144:147], v[218:221], v[80:83]
	s_setprio 0
	s_setprio 1
	v_mfma_f32_16x16x32_bf16 v[128:131], v[148:151], v[182:185], v[128:131]
	v_mfma_f32_16x16x32_bf16 v[128:131], v[152:155], v[186:189], v[128:131]
	v_mfma_f32_16x16x32_bf16 v[44:47], v[174:177], v[182:185], v[44:47]
	v_mfma_f32_16x16x32_bf16 v[44:47], v[178:181], v[186:189], v[44:47]
	v_mfma_f32_16x16x32_bf16 v[124:127], v[148:151], v[190:193], v[124:127]
	v_mfma_f32_16x16x32_bf16 v[124:127], v[152:155], v[194:197], v[124:127]
	v_mfma_f32_16x16x32_bf16 v[36:39], v[174:177], v[190:193], v[36:39]
	v_mfma_f32_16x16x32_bf16 v[36:39], v[178:181], v[194:197], v[36:39]
	v_mfma_f32_16x16x32_bf16 v[120:123], v[148:151], v[206:209], v[120:123]
	v_mfma_f32_16x16x32_bf16 v[120:123], v[152:155], v[210:213], v[120:123]
	v_mfma_f32_16x16x32_bf16 v[32:35], v[174:177], v[206:209], v[32:35]
	v_mfma_f32_16x16x32_bf16 v[32:35], v[178:181], v[210:213], v[32:35]
	s_setprio 2
	s_barrier
; #define PG8_STAGE(bufoff, gbase, voff) do { _Pragma("unroll") for (int _i = 0; _i < 2; ++_i) \
;         __builtin_amdgcn_global_load_lds((const unsigned*)((const char*)(gbase) + (voff)[_i]), (LAS unsigned*)(lds + (bufoff) + ldsw + _i * 8192), 16, 0, 0); } while (0)
; #define PG8_LDA(dst, b, h) do { _Pragma("unroll") for (int m = 0; m < 4; ++m) _Pragma("unroll") for (int k = 0; k < 2; ++k) dst[m][k] = *(const LAS bf16x8*)(lds + PG8_SA(b, h) + aoff + m * 2048 + k * 1024); } while (0)
; #define PG8_MMA(ai, bj, At, Bt) do { __builtin_amdgcn_s_setprio(1); _Pragma("unroll") for (int m = 0; m < 4; ++m) _Pragma("unroll") for (int n = 0; n < 2; ++n) _Pragma("unroll") for (int k = 0; k < 2; ++k) \
;         acc[ai][bj][m][n] = __builtin_amdgcn_mfma_f32_16x16x32_bf16(Bt[n][k], At[m][k], acc[ai][bj][m][n], 0, 0, 0); __builtin_amdgcn_s_setprio(0); } while (0)
; #define PG8_WAIT_V(n) asm volatile("s_waitcnt vmcnt(" #n ")" ::: "memory")
; #define PG8_WAIT_L(n) asm volatile("s_waitcnt lgkmcnt(" #n ")" ::: "memory")
; #define PG8_BAR __builtin_amdgcn_s_barrier()
; #define PG8_SCHED __builtin_amdgcn_sched_barrier(0)
; template <class Epi, class Sched, bool ALIGN_EPI = true>
; __device__ __forceinline__ void gemm_phase(LAS unsigned char* lds, const Gemm g, const Sched& S, const Epi& E) {
;     ...
;             PG8_WAIT_V(8); PG8_WAIT_L(0); PG8_BAR; PG8_MMA(0, 0, At, B0); PG8_MMA(0, 1, At, B1); PG8_BAR; PG8_SCHED;
;             PG8_LDA(At, 1, 1); PG8_STAGE(PG8_SB(1, 0), b3, voffB); PG8_STAGE(PG8_SB(1, 1), b3 + hB, voffB); PG8_STAGE(PG8_SA(1, 0), a3, voffA);
;             PG8_WAIT_V(8); PG8_WAIT_L(0); PG8_BAR; PG8_MMA(1, 0, At, B0); PG8_MMA(1, 1, At, B1); PG8_BAR; PG8_SCHED;
;         }
;         if constexpr (ALIGN_EPI) { if (wr == 0) PG8_BAR; }
	v_mfma_f32_16x16x32_bf16 v[112:115], v[148:151], v[214:217], v[112:115]
	v_mfma_f32_16x16x32_bf16 v[112:115], v[152:155], v[218:221], v[112:115]
	v_mfma_f32_16x16x32_bf16 v[28:31], v[174:177], v[214:217], v[28:31]
	v_mfma_f32_16x16x32_bf16 v[28:31], v[178:181], v[218:221], v[28:31]
	s_setprio 0
	s_add_i32 s26, s30, s61
	v_lshl_add_u64 v[156:157], v[156:157], 0, s[86:87]
	s_mov_b32 m0, s26
	ds_read_b128 v[182:185], v205 offset:49152
	ds_read_b128 v[186:189], v205 offset:50176
	ds_read_b128 v[190:193], v205 offset:51200
	ds_read_b128 v[194:197], v205 offset:52224
	ds_read_b128 v[206:209], v205 offset:53248
	ds_read_b128 v[210:213], v205 offset:54272
	ds_read_b128 v[214:217], v205 offset:55296
	ds_read_b128 v[218:221], v205 offset:56320
	global_load_lds_dwordx4 v[156:157], off
	s_add_i32 m0, s26, 0x2000
	s_add_u32 s26, s44, 0x80080
	v_lshl_add_u64 v[156:157], v[160:161], 0, s[86:87]
	s_addc_u32 s27, s45, 0
	s_add_i32 s30, s31, s61
	global_load_lds_dwordx4 v[156:157], off
	v_lshl_add_u64 v[156:157], s[26:27], 0, v[166:167]
	s_mov_b32 m0, s30
	s_nop 0
	global_load_lds_dwordx4 v[156:157], off
	v_lshl_add_u64 v[156:157], s[26:27], 0, v[0:1]
	s_add_i32 m0, s30, 0x2000
	s_nop 0
	global_load_lds_dwordx4 v[156:157], off
	v_lshl_add_u64 v[156:157], v[162:163], 0, s[86:87]
	s_mov_b32 m0, s75
	s_nop 0
	global_load_lds_dwordx4 v[156:157], off
	v_lshl_add_u64 v[156:157], v[222:223], 0, s[86:87]
	s_mov_b32 m0, s76
	s_nop 0
	global_load_lds_dwordx4 v[156:157], off
	s_waitcnt vmcnt(8)
	s_waitcnt lgkmcnt(0)
	s_barrier
	s_setprio 1
	s_waitcnt lgkmcnt(0)
	v_mfma_f32_16x16x32_bf16 v[60:63], v[132:135], v[182:185], v[60:63]
	v_mfma_f32_16x16x32_bf16 v[60:63], v[136:139], v[186:189], v[60:63]
	v_mfma_f32_16x16x32_bf16 v[68:71], v[140:143], v[182:185], v[68:71]
	v_mfma_f32_16x16x32_bf16 v[68:71], v[144:147], v[186:189], v[68:71]
	v_mfma_f32_16x16x32_bf16 v[40:43], v[132:135], v[190:193], v[40:43]
	v_mfma_f32_16x16x32_bf16 v[40:43], v[136:139], v[194:197], v[40:43]
	v_mfma_f32_16x16x32_bf16 v[64:67], v[140:143], v[190:193], v[64:67]
	v_mfma_f32_16x16x32_bf16 v[64:67], v[144:147], v[194:197], v[64:67]
	v_mfma_f32_16x16x32_bf16 v[24:27], v[132:135], v[206:209], v[24:27]
	v_mfma_f32_16x16x32_bf16 v[24:27], v[136:139], v[210:213], v[24:27]
	v_mfma_f32_16x16x32_bf16 v[56:59], v[140:143], v[206:209], v[56:59]
	v_mfma_f32_16x16x32_bf16 v[56:59], v[144:147], v[210:213], v[56:59]
	v_mfma_f32_16x16x32_bf16 v[12:15], v[132:135], v[214:217], v[12:15]
	v_mfma_f32_16x16x32_bf16 v[12:15], v[136:139], v[218:221], v[12:15]
	v_mfma_f32_16x16x32_bf16 v[48:51], v[140:143], v[214:217], v[48:51]
	v_mfma_f32_16x16x32_bf16 v[48:51], v[144:147], v[218:221], v[48:51]
	s_setprio 0
	s_setprio 1
	v_mfma_f32_16x16x32_bf16 v[104:107], v[148:151], v[182:185], v[104:107]
	v_mfma_f32_16x16x32_bf16 v[104:107], v[152:155], v[186:189], v[104:107]
	v_mfma_f32_16x16x32_bf16 v[20:23], v[174:177], v[182:185], v[20:23]
	v_mfma_f32_16x16x32_bf16 v[20:23], v[178:181], v[186:189], v[20:23]
	v_mfma_f32_16x16x32_bf16 v[92:95], v[148:151], v[190:193], v[92:95]
	v_mfma_f32_16x16x32_bf16 v[92:95], v[152:155], v[194:197], v[92:95]
	v_mfma_f32_16x16x32_bf16 v[16:19], v[174:177], v[190:193], v[16:19]
	v_mfma_f32_16x16x32_bf16 v[16:19], v[178:181], v[194:197], v[16:19]
	v_mfma_f32_16x16x32_bf16 v[76:79], v[148:151], v[206:209], v[76:79]
	v_mfma_f32_16x16x32_bf16 v[76:79], v[152:155], v[210:213], v[76:79]
	v_mfma_f32_16x16x32_bf16 v[8:11], v[174:177], v[206:209], v[8:11]
	v_mfma_f32_16x16x32_bf16 v[8:11], v[178:181], v[210:213], v[8:11]
	s_setprio 2
	s_barrier
	v_mfma_f32_16x16x32_bf16 v[52:55], v[148:151], v[214:217], v[52:55]
	v_mfma_f32_16x16x32_bf16 v[52:55], v[152:155], v[218:221], v[52:55]
	v_mfma_f32_16x16x32_bf16 v[4:7], v[174:177], v[214:217], v[4:7]
	v_mfma_f32_16x16x32_bf16 v[4:7], v[178:181], v[218:221], v[4:7]
	s_setprio 0
	s_add_i32 s25, s25, 2
	s_add_u32 s6, s6, 0x100
	s_addc_u32 s7, s7, 0
	s_add_u32 s19, s19, 0x100
	s_addc_u32 s24, s24, 0
	s_cmp_gt_u32 s25, 29
	s_cbranch_scc0 .LBB0_828
	s_and_b64 vcc, exec, s[12:13]
	s_cbranch_vccz .LBB0_831
	s_barrier

; #define PG8_STAGE(bufoff, gbase, voff) do { _Pragma("unroll") for (int _i = 0; _i < 2; ++_i) \
;         __builtin_amdgcn_global_load_lds((const unsigned*)((const char*)(gbase) + (voff)[_i]), (LAS unsigned*)(lds + (bufoff) + ldsw + _i * 8192), 16, 0, 0); } while (0)
; #define PG8_LDA(dst, b, h) do { _Pragma("unroll") for (int m = 0; m < 4; ++m) _Pragma("unroll") for (int k = 0; k < 2; ++k) dst[m][k] = *(const LAS bf16x8*)(lds + PG8_SA(b, h) + aoff + m * 2048 + k * 1024); } while (0)
; #define PG8_LDB(dst, b, h) do { _Pragma("unroll") for (int n = 0; n < 2; ++n) _Pragma("unroll") for (int k = 0; k < 2; ++k) dst[n][k] = *(const LAS bf16x8*)(lds + PG8_SB(b, h) + boff + n * 2048 + k * 1024); } while (0)
; #define PG8_MMA(ai, bj, At, Bt) do { __builtin_amdgcn_s_setprio(1); _Pragma("unroll") for (int m = 0; m < 4; ++m) _Pragma("unroll") for (int n = 0; n < 2; ++n) _Pragma("unroll") for (int k = 0; k < 2; ++k) \
;         acc[ai][bj][m][n] = __builtin_amdgcn_mfma_f32_16x16x32_bf16(Bt[n][k], At[m][k], acc[ai][bj][m][n], 0, 0, 0); __builtin_amdgcn_s_setprio(0); } while (0)
; #define PG8_WAIT_V(n) asm volatile("s_waitcnt vmcnt(" #n ")" ::: "memory")
; #define PG8_WAIT_L(n) asm volatile("s_waitcnt lgkmcnt(" #n ")" ::: "memory")
; #define PG8_BAR __builtin_amdgcn_s_barrier()
; #define PG8_SCHED __builtin_amdgcn_sched_barrier(0)
; template <class Epi, class Sched, bool ALIGN_EPI = true>
; __device__ __forceinline__ void gemm_phase(LAS unsigned char* lds, const Gemm g, const Sched& S, const Epi& E) {
;     ...
;             const bool last = (t == nt - 2);
;             const char* a1 = cA + (size_t)(t + 1) * kstep;
;             const char* a2 = last ? nA : cA + (size_t)(t + 2) * kstep; const char* b2 = last ? nB : cB + (size_t)(t + 2) * kstep;
;             const char* a3 = a2 + kstep; const char* b3 = b2 + kstep;
;             PG8_LDB(B0, 0, 0); PG8_LDB(B1, 0, 1); PG8_SCHED; PG8_LDA(At, 0, 0); PG8_STAGE(PG8_SA(1, 1), a1 + hA, voffA);
;             PG8_WAIT_V(8); PG8_WAIT_L(0); PG8_BAR; PG8_MMA(0, 0, At, B0); PG8_MMA(0, 1, At, B1); PG8_BAR; PG8_SCHED;
;             PG8_LDA(At, 0, 1); PG8_STAGE(PG8_SB(0, 0), b2, voffB); PG8_STAGE(PG8_SB(0, 1), b2 + hB, voffB); PG8_STAGE(PG8_SA(0, 0), a2, voffA);
;             PG8_WAIT_V(8); PG8_WAIT_L(0); PG8_BAR; PG8_MMA(1, 0, At, B0); PG8_MMA(1, 1, At, B1); PG8_BAR; PG8_SCHED;
.LBB0_1111:
	s_add_u32 vcc_lo, s10, 0x100
	s_addc_u32 vcc_hi, s11, 0
	s_add_u32 s19, s16, s10
	s_addc_u32 s24, s17, s11
	s_add_i32 s25, 0, 0x10000
	s_cmpk_eq_i32 s18, 0x54
	s_cselect_b32 s65, s61, s24
	s_cselect_b32 s24, 0, vcc_lo
	s_cselect_b32 s64, s60, s19
	s_cselect_b32 s19, 0, vcc_hi
	s_add_u32 s62, s2, s24
	v_add_u32_e32 v160, s25, v188
	s_addc_u32 s63, s3, s19
	s_add_i32 s19, 0, 0x14000
	ds_read_b128 v[136:139], v160
	ds_read_b128 v[140:143], v160 offset:1024
	ds_read_b128 v[144:147], v160 offset:2048
	ds_read_b128 v[172:175], v160 offset:3072
	v_add_u32_e32 v160, s19, v188
	ds_read_b128 v[176:179], v160
	ds_read_b128 v[180:183], v160 offset:1024
	ds_read_b128 v[184:187], v160 offset:2048
	ds_read_b128 v[208:211], v160 offset:3072
	v_lshl_add_u64 v[160:161], v[132:133], 0, s[10:11]
	s_add_i32 m0, s67, 0xc000
	ds_read_b128 v[212:215], v197
	ds_read_b128 v[216:219], v197 offset:1024
	ds_read_b128 v[220:223], v197 offset:2048
	ds_read_b128 v[224:227], v197 offset:3072
	ds_read_b128 v[228:231], v197 offset:4096
	ds_read_b128 v[232:235], v197 offset:5120
	ds_read_b128 v[236:239], v197 offset:6144
	ds_read_b128 v[240:243], v197 offset:7168
	global_load_lds_dwordx4 v[160:161], off
	v_lshl_add_u64 v[160:161], v[134:135], 0, s[10:11]
	s_add_i32 m0, s67, 0xe000
	s_nop 0
	global_load_lds_dwordx4 v[160:161], off
	s_waitcnt vmcnt(8)
	s_waitcnt lgkmcnt(0)
	s_barrier
	s_setprio 1
	s_waitcnt lgkmcnt(0)
	v_mfma_f32_16x16x32_bf16 v[16:19], v[136:139], v[212:215], v[16:19]
	v_mfma_f32_16x16x32_bf16 v[16:19], v[140:143], v[216:219], v[16:19]
	v_mfma_f32_16x16x32_bf16 v[12:15], v[144:147], v[212:215], v[12:15]
	v_mfma_f32_16x16x32_bf16 v[12:15], v[172:175], v[216:219], v[12:15]
	v_mfma_f32_16x16x32_bf16 v[56:59], v[136:139], v[220:223], v[56:59]
	v_mfma_f32_16x16x32_bf16 v[56:59], v[140:143], v[224:227], v[56:59]
	v_mfma_f32_16x16x32_bf16 v[52:55], v[144:147], v[220:223], v[52:55]
	v_mfma_f32_16x16x32_bf16 v[52:55], v[172:175], v[224:227], v[52:55]
	v_mfma_f32_16x16x32_bf16 v[88:91], v[136:139], v[228:231], v[88:91]
	v_mfma_f32_16x16x32_bf16 v[88:91], v[140:143], v[232:235], v[88:91]
	v_mfma_f32_16x16x32_bf16 v[76:79], v[144:147], v[228:231], v[76:79]
	v_mfma_f32_16x16x32_bf16 v[76:79], v[172:175], v[232:235], v[76:79]
	v_mfma_f32_16x16x32_bf16 v[112:115], v[136:139], v[236:239], v[112:115]
	v_mfma_f32_16x16x32_bf16 v[112:115], v[140:143], v[240:243], v[112:115]
	v_mfma_f32_16x16x32_bf16 v[108:111], v[144:147], v[236:239], v[108:111]
	v_mfma_f32_16x16x32_bf16 v[108:111], v[172:175], v[240:243], v[108:111]
	s_setprio 0
	s_setprio 1
	v_mfma_f32_16x16x32_bf16 v[8:11], v[176:179], v[212:215], v[8:11]
	v_mfma_f32_16x16x32_bf16 v[8:11], v[180:183], v[216:219], v[8:11]
	v_mfma_f32_16x16x32_bf16 v[4:7], v[184:187], v[212:215], v[4:7]
	v_mfma_f32_16x16x32_bf16 v[4:7], v[208:211], v[216:219], v[4:7]
	v_mfma_f32_16x16x32_bf16 v[40:43], v[176:179], v[220:223], v[40:43]
	v_mfma_f32_16x16x32_bf16 v[40:43], v[180:183], v[224:227], v[40:43]
	v_mfma_f32_16x16x32_bf16 v[36:39], v[184:187], v[220:223], v[36:39]
	v_mfma_f32_16x16x32_bf16 v[36:39], v[208:211], v[224:227], v[36:39]
	v_mfma_f32_16x16x32_bf16 v[64:67], v[176:179], v[228:231], v[64:67]
	v_mfma_f32_16x16x32_bf16 v[64:67], v[180:183], v[232:235], v[64:67]
	v_mfma_f32_16x16x32_bf16 v[60:63], v[184:187], v[228:231], v[60:63]
	v_mfma_f32_16x16x32_bf16 v[60:63], v[208:211], v[232:235], v[60:63]
	s_setprio 2
	s_barrier
	v_mfma_f32_16x16x32_bf16 v[96:99], v[176:179], v[236:239], v[96:99]
	v_mfma_f32_16x16x32_bf16 v[96:99], v[180:183], v[240:243], v[96:99]
	v_mfma_f32_16x16x32_bf16 v[92:95], v[184:187], v[236:239], v[92:95]
	v_mfma_f32_16x16x32_bf16 v[92:95], v[208:211], v[240:243], v[92:95]
	s_setprio 0
	s_add_i32 s10, s25, s66
	v_lshl_add_u64 v[160:161], s[62:63], 0, v[2:3]
	s_mov_b32 m0, s10
	ds_read_b128 v[212:215], v197 offset:16384
	ds_read_b128 v[216:219], v197 offset:17408
	ds_read_b128 v[220:223], v197 offset:18432
	ds_read_b128 v[224:227], v197 offset:19456
	ds_read_b128 v[228:231], v197 offset:20480
	ds_read_b128 v[232:235], v197 offset:21504
	ds_read_b128 v[236:239], v197 offset:22528
	ds_read_b128 v[240:243], v197 offset:23552
	global_load_lds_dwordx4 v[160:161], off
	s_add_i32 m0, s10, 0x2000
	s_add_u32 s10, s62, 0x160000
	v_lshl_add_u64 v[162:163], s[62:63], 0, v[150:151]
	s_addc_u32 s11, s63, 0
	s_add_i32 s19, s19, s66
	global_load_lds_dwordx4 v[162:163], off
	v_lshl_add_u64 v[244:245], s[10:11], 0, v[2:3]
	s_mov_b32 m0, s19
	v_lshl_add_u64 v[246:247], s[64:65], 0, v[148:149]
	global_load_lds_dwordx4 v[244:245], off
	v_lshl_add_u64 v[244:245], s[10:11], 0, v[150:151]
	s_add_i32 m0, s19, 0x2000
	s_nop 0
	global_load_lds_dwordx4 v[244:245], off
	v_lshl_add_u64 v[244:245], s[64:65], 0, v[0:1]
	s_mov_b32 m0, s67
	s_nop 0
	global_load_lds_dwordx4 v[244:245], off
	s_mov_b32 m0, s75
	s_nop 0
	global_load_lds_dwordx4 v[246:247], off
	s_waitcnt vmcnt(8)
	s_waitcnt lgkmcnt(0)
	s_barrier
; #define PG8_STAGE(bufoff, gbase, voff) do { _Pragma("unroll") for (int _i = 0; _i < 2; ++_i) \
;         __builtin_amdgcn_global_load_lds((const unsigned*)((const char*)(gbase) + (voff)[_i]), (LAS unsigned*)(lds + (bufoff) + ldsw + _i * 8192), 16, 0, 0); } while (0)
; #define PG8_LDA(dst, b, h) do { _Pragma("unroll") for (int m = 0; m < 4; ++m) _Pragma("unroll") for (int k = 0; k < 2; ++k) dst[m][k] = *(const LAS bf16x8*)(lds + PG8_SA(b, h) + aoff + m * 2048 + k * 1024); } while (0)
; #define PG8_LDB(dst, b, h) do { _Pragma("unroll") for (int n = 0; n < 2; ++n) _Pragma("unroll") for (int k = 0; k < 2; ++k) dst[n][k] = *(const LAS bf16x8*)(lds + PG8_SB(b, h) + boff + n * 2048 + k * 1024); } while (0)
; #define PG8_MMA(ai, bj, At, Bt) do { __builtin_amdgcn_s_setprio(1); _Pragma("unroll") for (int m = 0; m < 4; ++m) _Pragma("unroll") for (int n = 0; n < 2; ++n) _Pragma("unroll") for (int k = 0; k < 2; ++k) \
;         acc[ai][bj][m][n] = __builtin_amdgcn_mfma_f32_16x16x32_bf16(Bt[n][k], At[m][k], acc[ai][bj][m][n], 0, 0, 0); __builtin_amdgcn_s_setprio(0); } while (0)
; #define PG8_WAIT_V(n) asm volatile("s_waitcnt vmcnt(" #n ")" ::: "memory")
; #define PG8_WAIT_L(n) asm volatile("s_waitcnt lgkmcnt(" #n ")" ::: "memory")
; #define PG8_BAR __builtin_amdgcn_s_barrier()
; #define PG8_SCHED __builtin_amdgcn_sched_barrier(0)
; template <class Epi, class Sched, bool ALIGN_EPI = true>
; __device__ __forceinline__ void gemm_phase(LAS unsigned char* lds, const Gemm g, const Sched& S, const Epi& E) {
;     ...
;             PG8_WAIT_V(8); PG8_WAIT_L(0); PG8_BAR; PG8_MMA(1, 0, At, B0); PG8_MMA(1, 1, At, B1); PG8_BAR; PG8_SCHED;
;             PG8_LDB(B0, 1, 0); PG8_LDB(B1, 1, 1); PG8_SCHED; PG8_LDA(At, 1, 0); PG8_STAGE(PG8_SA(0, 1), a2 + hA, voffA);
;             PG8_WAIT_V(8); PG8_WAIT_L(0); PG8_BAR; PG8_MMA(0, 0, At, B0); PG8_MMA(0, 1, At, B1); PG8_BAR; PG8_SCHED;
	s_setprio 1
	s_waitcnt lgkmcnt(0)
	v_mfma_f32_16x16x32_bf16 v[128:131], v[136:139], v[212:215], v[128:131]
	v_mfma_f32_16x16x32_bf16 v[128:131], v[140:143], v[216:219], v[128:131]
	v_mfma_f32_16x16x32_bf16 v[124:127], v[144:147], v[212:215], v[124:127]
	v_mfma_f32_16x16x32_bf16 v[124:127], v[172:175], v[216:219], v[124:127]
	v_mfma_f32_16x16x32_bf16 v[104:107], v[136:139], v[220:223], v[104:107]
	v_mfma_f32_16x16x32_bf16 v[104:107], v[140:143], v[224:227], v[104:107]
	v_mfma_f32_16x16x32_bf16 v[100:103], v[144:147], v[220:223], v[100:103]
	v_mfma_f32_16x16x32_bf16 v[100:103], v[172:175], v[224:227], v[100:103]
	v_mfma_f32_16x16x32_bf16 v[72:75], v[136:139], v[228:231], v[72:75]
	v_mfma_f32_16x16x32_bf16 v[72:75], v[140:143], v[232:235], v[72:75]
	v_mfma_f32_16x16x32_bf16 v[68:71], v[144:147], v[228:231], v[68:71]
	v_mfma_f32_16x16x32_bf16 v[68:71], v[172:175], v[232:235], v[68:71]
	v_mfma_f32_16x16x32_bf16 v[32:35], v[136:139], v[236:239], v[32:35]
	v_mfma_f32_16x16x32_bf16 v[32:35], v[140:143], v[240:243], v[32:35]
	v_mfma_f32_16x16x32_bf16 v[28:31], v[144:147], v[236:239], v[28:31]
	v_mfma_f32_16x16x32_bf16 v[28:31], v[172:175], v[240:243], v[28:31]
	s_setprio 0
	s_setprio 1
	v_mfma_f32_16x16x32_bf16 v[120:123], v[176:179], v[212:215], v[120:123]
	v_mfma_f32_16x16x32_bf16 v[120:123], v[180:183], v[216:219], v[120:123]
	v_mfma_f32_16x16x32_bf16 v[116:119], v[184:187], v[212:215], v[116:119]
	v_mfma_f32_16x16x32_bf16 v[116:119], v[208:211], v[216:219], v[116:119]
	v_mfma_f32_16x16x32_bf16 v[84:87], v[176:179], v[220:223], v[84:87]
	v_mfma_f32_16x16x32_bf16 v[84:87], v[180:183], v[224:227], v[84:87]
	v_mfma_f32_16x16x32_bf16 v[80:83], v[184:187], v[220:223], v[80:83]
	v_mfma_f32_16x16x32_bf16 v[80:83], v[208:211], v[224:227], v[80:83]
	v_mfma_f32_16x16x32_bf16 v[48:51], v[176:179], v[228:231], v[48:51]
	v_mfma_f32_16x16x32_bf16 v[48:51], v[180:183], v[232:235], v[48:51]
	v_mfma_f32_16x16x32_bf16 v[44:47], v[184:187], v[228:231], v[44:47]
	v_mfma_f32_16x16x32_bf16 v[44:47], v[208:211], v[232:235], v[44:47]
	s_setprio 2
	s_barrier
	v_mfma_f32_16x16x32_bf16 v[24:27], v[176:179], v[236:239], v[24:27]
	v_mfma_f32_16x16x32_bf16 v[24:27], v[180:183], v[240:243], v[24:27]
	v_mfma_f32_16x16x32_bf16 v[20:23], v[184:187], v[236:239], v[20:23]
	v_mfma_f32_16x16x32_bf16 v[20:23], v[208:211], v[240:243], v[20:23]
	s_setprio 0
	s_add_i32 s19, 0, 0x18000
	s_add_i32 s24, 0, 0x1c000
	v_add_u32_e32 v172, s19, v188
	v_add_u32_e32 v207, s24, v188
	ds_read_b128 v[136:139], v172
	ds_read_b128 v[140:143], v172 offset:1024
	ds_read_b128 v[144:147], v172 offset:2048
	ds_read_b128 v[172:175], v172 offset:3072
	ds_read_b128 v[176:179], v207
	ds_read_b128 v[180:183], v207 offset:1024
	ds_read_b128 v[184:187], v207 offset:2048
	ds_read_b128 v[208:211], v207 offset:3072
	s_add_u32 s10, s64, 0x160000
	s_addc_u32 s11, s65, 0
	s_mov_b32 m0, s76
	v_lshl_add_u64 v[248:249], s[10:11], 0, v[0:1]
	ds_read_b128 v[212:215], v197 offset:32768
	ds_read_b128 v[216:219], v197 offset:33792
	ds_read_b128 v[220:223], v197 offset:34816
	ds_read_b128 v[224:227], v197 offset:35840
	ds_read_b128 v[228:231], v197 offset:36864
	ds_read_b128 v[232:235], v197 offset:37888
	ds_read_b128 v[236:239], v197 offset:38912
	ds_read_b128 v[240:243], v197 offset:39936
	global_load_lds_dwordx4 v[248:249], off
	v_lshl_add_u64 v[248:249], s[10:11], 0, v[148:149]
	s_mov_b32 m0, s77
	s_nop 0
	global_load_lds_dwordx4 v[248:249], off
	s_waitcnt vmcnt(8)
	s_waitcnt lgkmcnt(0)
	s_barrier
	s_setprio 1
	s_waitcnt lgkmcnt(0)
	v_mfma_f32_16x16x32_bf16 v[16:19], v[136:139], v[212:215], v[16:19]
	v_mfma_f32_16x16x32_bf16 v[16:19], v[140:143], v[216:219], v[16:19]
	v_mfma_f32_16x16x32_bf16 v[12:15], v[144:147], v[212:215], v[12:15]
	v_mfma_f32_16x16x32_bf16 v[12:15], v[172:175], v[216:219], v[12:15]
	v_mfma_f32_16x16x32_bf16 v[56:59], v[136:139], v[220:223], v[56:59]
	v_mfma_f32_16x16x32_bf16 v[56:59], v[140:143], v[224:227], v[56:59]
	v_mfma_f32_16x16x32_bf16 v[52:55], v[144:147], v[220:223], v[52:55]
	v_mfma_f32_16x16x32_bf16 v[52:55], v[172:175], v[224:227], v[52:55]
	v_mfma_f32_16x16x32_bf16 v[88:91], v[136:139], v[228:231], v[88:91]
	v_mfma_f32_16x16x32_bf16 v[88:91], v[140:143], v[232:235], v[88:91]
	v_mfma_f32_16x16x32_bf16 v[76:79], v[144:147], v[228:231], v[76:79]
	v_mfma_f32_16x16x32_bf16 v[76:79], v[172:175], v[232:235], v[76:79]
	v_mfma_f32_16x16x32_bf16 v[112:115], v[136:139], v[236:239], v[112:115]
	v_mfma_f32_16x16x32_bf16 v[112:115], v[140:143], v[240:243], v[112:115]
	v_mfma_f32_16x16x32_bf16 v[108:111], v[144:147], v[236:239], v[108:111]
	v_mfma_f32_16x16x32_bf16 v[108:111], v[172:175], v[240:243], v[108:111]
	s_setprio 0
	s_setprio 1
	v_mfma_f32_16x16x32_bf16 v[8:11], v[176:179], v[212:215], v[8:11]
	v_mfma_f32_16x16x32_bf16 v[8:11], v[180:183], v[216:219], v[8:11]
	v_mfma_f32_16x16x32_bf16 v[4:7], v[184:187], v[212:215], v[4:7]
	v_mfma_f32_16x16x32_bf16 v[4:7], v[208:211], v[216:219], v[4:7]
	v_mfma_f32_16x16x32_bf16 v[40:43], v[176:179], v[220:223], v[40:43]
	v_mfma_f32_16x16x32_bf16 v[40:43], v[180:183], v[224:227], v[40:43]
	v_mfma_f32_16x16x32_bf16 v[36:39], v[184:187], v[220:223], v[36:39]
	v_mfma_f32_16x16x32_bf16 v[36:39], v[208:211], v[224:227], v[36:39]
	v_mfma_f32_16x16x32_bf16 v[64:67], v[176:179], v[228:231], v[64:67]
	v_mfma_f32_16x16x32_bf16 v[64:67], v[180:183], v[232:235], v[64:67]
	v_mfma_f32_16x16x32_bf16 v[60:63], v[184:187], v[228:231], v[60:63]
	v_mfma_f32_16x16x32_bf16 v[60:63], v[208:211], v[232:235], v[60:63]
	s_setprio 2
	s_barrier
; #define PG8_STAGE(bufoff, gbase, voff) do { _Pragma("unroll") for (int _i = 0; _i < 2; ++_i) \
;         __builtin_amdgcn_global_load_lds((const unsigned*)((const char*)(gbase) + (voff)[_i]), (LAS unsigned*)(lds + (bufoff) + ldsw + _i * 8192), 16, 0, 0); } while (0)
; #define PG8_LDA(dst, b, h) do { _Pragma("unroll") for (int m = 0; m < 4; ++m) _Pragma("unroll") for (int k = 0; k < 2; ++k) dst[m][k] = *(const LAS bf16x8*)(lds + PG8_SA(b, h) + aoff + m * 2048 + k * 1024); } while (0)
; #define PG8_MMA(ai, bj, At, Bt) do { __builtin_amdgcn_s_setprio(1); _Pragma("unroll") for (int m = 0; m < 4; ++m) _Pragma("unroll") for (int n = 0; n < 2; ++n) _Pragma("unroll") for (int k = 0; k < 2; ++k) \
;         acc[ai][bj][m][n] = __builtin_amdgcn_mfma_f32_16x16x32_bf16(Bt[n][k], At[m][k], acc[ai][bj][m][n], 0, 0, 0); __builtin_amdgcn_s_setprio(0); } while (0)
; #define PG8_WAIT_V(n) asm volatile("s_waitcnt vmcnt(" #n ")" ::: "memory")
; #define PG8_WAIT_L(n) asm volatile("s_waitcnt lgkmcnt(" #n ")" ::: "memory")
; #define PG8_BAR __builtin_amdgcn_s_barrier()
; #define PG8_SCHED __builtin_amdgcn_sched_barrier(0)
; template <class Epi, class Sched, bool ALIGN_EPI = true>
; __device__ __forceinline__ void gemm_phase(LAS unsigned char* lds, const Gemm g, const Sched& S, const Epi& E) {
;     ...
;             PG8_WAIT_V(8); PG8_WAIT_L(0); PG8_BAR; PG8_MMA(0, 0, At, B0); PG8_MMA(0, 1, At, B1); PG8_BAR; PG8_SCHED;
;             PG8_LDA(At, 1, 1); PG8_STAGE(PG8_SB(1, 0), b3, voffB); PG8_STAGE(PG8_SB(1, 1), b3 + hB, voffB); PG8_STAGE(PG8_SA(1, 0), a3, voffA);
;             PG8_WAIT_V(8); PG8_WAIT_L(0); PG8_BAR; PG8_MMA(1, 0, At, B0); PG8_MMA(1, 1, At, B1); PG8_BAR; PG8_SCHED;
;         }
;         if constexpr (ALIGN_EPI) { if (wr == 0) PG8_BAR; }
	v_mfma_f32_16x16x32_bf16 v[96:99], v[176:179], v[236:239], v[96:99]
	v_mfma_f32_16x16x32_bf16 v[96:99], v[180:183], v[240:243], v[96:99]
	v_mfma_f32_16x16x32_bf16 v[92:95], v[184:187], v[236:239], v[92:95]
	v_mfma_f32_16x16x32_bf16 v[92:95], v[208:211], v[240:243], v[92:95]
	s_setprio 0
	s_add_i32 s10, s19, s66
	v_lshl_add_u64 v[160:161], v[160:161], 0, s[86:87]
	s_mov_b32 m0, s10
	ds_read_b128 v[212:215], v197 offset:49152
	ds_read_b128 v[216:219], v197 offset:50176
	ds_read_b128 v[220:223], v197 offset:51200
	ds_read_b128 v[224:227], v197 offset:52224
	ds_read_b128 v[228:231], v197 offset:53248
	ds_read_b128 v[232:235], v197 offset:54272
	ds_read_b128 v[236:239], v197 offset:55296
	ds_read_b128 v[240:243], v197 offset:56320
	global_load_lds_dwordx4 v[160:161], off
	s_add_i32 m0, s10, 0x2000
	s_add_u32 s10, s62, 0x160080
	v_lshl_add_u64 v[160:161], v[162:163], 0, s[86:87]
	s_addc_u32 s11, s63, 0
	s_add_i32 s19, s24, s66
	global_load_lds_dwordx4 v[160:161], off
	v_lshl_add_u64 v[160:161], s[10:11], 0, v[2:3]
	s_mov_b32 m0, s19
	s_nop 0
	global_load_lds_dwordx4 v[160:161], off
	v_lshl_add_u64 v[160:161], s[10:11], 0, v[150:151]
	s_add_i32 m0, s19, 0x2000
	s_nop 0
	global_load_lds_dwordx4 v[160:161], off
	v_lshl_add_u64 v[160:161], v[244:245], 0, s[86:87]
	s_mov_b32 m0, s80
	s_nop 0
	global_load_lds_dwordx4 v[160:161], off
	v_lshl_add_u64 v[160:161], v[246:247], 0, s[86:87]
	s_mov_b32 m0, s81
	s_nop 0
	global_load_lds_dwordx4 v[160:161], off
	s_waitcnt vmcnt(8)
	s_waitcnt lgkmcnt(0)
	s_barrier
	s_setprio 1
	s_waitcnt lgkmcnt(0)
	v_mfma_f32_16x16x32_bf16 v[128:131], v[136:139], v[212:215], v[128:131]
	v_mfma_f32_16x16x32_bf16 v[128:131], v[140:143], v[216:219], v[128:131]
	v_mfma_f32_16x16x32_bf16 v[124:127], v[144:147], v[212:215], v[124:127]
	v_mfma_f32_16x16x32_bf16 v[124:127], v[172:175], v[216:219], v[124:127]
	v_mfma_f32_16x16x32_bf16 v[104:107], v[136:139], v[220:223], v[104:107]
	v_mfma_f32_16x16x32_bf16 v[104:107], v[140:143], v[224:227], v[104:107]
	v_mfma_f32_16x16x32_bf16 v[100:103], v[144:147], v[220:223], v[100:103]
	v_mfma_f32_16x16x32_bf16 v[100:103], v[172:175], v[224:227], v[100:103]
	v_mfma_f32_16x16x32_bf16 v[72:75], v[136:139], v[228:231], v[72:75]
	v_mfma_f32_16x16x32_bf16 v[72:75], v[140:143], v[232:235], v[72:75]
	v_mfma_f32_16x16x32_bf16 v[68:71], v[144:147], v[228:231], v[68:71]
	v_mfma_f32_16x16x32_bf16 v[68:71], v[172:175], v[232:235], v[68:71]
	v_mfma_f32_16x16x32_bf16 v[32:35], v[136:139], v[236:239], v[32:35]
	v_mfma_f32_16x16x32_bf16 v[32:35], v[140:143], v[240:243], v[32:35]
	v_mfma_f32_16x16x32_bf16 v[28:31], v[144:147], v[236:239], v[28:31]
	v_mfma_f32_16x16x32_bf16 v[28:31], v[172:175], v[240:243], v[28:31]
	s_setprio 0
	s_setprio 1
	v_mfma_f32_16x16x32_bf16 v[120:123], v[176:179], v[212:215], v[120:123]
	v_mfma_f32_16x16x32_bf16 v[120:123], v[180:183], v[216:219], v[120:123]
	v_mfma_f32_16x16x32_bf16 v[116:119], v[184:187], v[212:215], v[116:119]
	v_mfma_f32_16x16x32_bf16 v[116:119], v[208:211], v[216:219], v[116:119]
	v_mfma_f32_16x16x32_bf16 v[84:87], v[176:179], v[220:223], v[84:87]
	v_mfma_f32_16x16x32_bf16 v[84:87], v[180:183], v[224:227], v[84:87]
	v_mfma_f32_16x16x32_bf16 v[80:83], v[184:187], v[220:223], v[80:83]
	v_mfma_f32_16x16x32_bf16 v[80:83], v[208:211], v[224:227], v[80:83]
	v_mfma_f32_16x16x32_bf16 v[48:51], v[176:179], v[228:231], v[48:51]
	v_mfma_f32_16x16x32_bf16 v[48:51], v[180:183], v[232:235], v[48:51]
	v_mfma_f32_16x16x32_bf16 v[44:47], v[184:187], v[228:231], v[44:47]
	v_mfma_f32_16x16x32_bf16 v[44:47], v[208:211], v[232:235], v[44:47]
	s_setprio 2
	s_barrier
	v_mfma_f32_16x16x32_bf16 v[24:27], v[176:179], v[236:239], v[24:27]
	v_mfma_f32_16x16x32_bf16 v[24:27], v[180:183], v[240:243], v[24:27]
	v_mfma_f32_16x16x32_bf16 v[20:23], v[184:187], v[236:239], v[20:23]
	v_mfma_f32_16x16x32_bf16 v[20:23], v[208:211], v[240:243], v[20:23]
	s_setprio 0
	s_add_i32 s18, s18, 2
	s_cmpk_gt_u32 s18, 0x55
	s_mov_b64 s[10:11], vcc
	s_cbranch_scc0 .LBB0_1111
	s_and_b64 vcc, exec, s[42:43]
	s_cbranch_vccz .LBB0_1114
	s_barrier
